# attention: V^T tile rows 144 B apart, keys of a PV k-step contiguous: PV operand reads are ds_read_b128 instead of ds_read2_b64
# speedup vs baseline: 1.0058x; 1.0018x over previous
; DI unsigned pk2(float a, float b) { f32x2 f = {a, b}; bf16v2 r = __builtin_convertvector(f, bf16v2); return __builtin_bit_cast(unsigned, r); }
; #define VLD(dst, j, dt) do { LAS unsigned char* va_ = vb + (32 * (dt) + n) * VROW + (16 * (j) + 4 * g) * 2; const u32x2 lo_ = *(const LAS u32x2*)(va_), hi_ = *(const LAS u32x2*)(va_ + 16); dst = (u32x4){lo_.x, lo_.y, hi_.x, hi_.y}; } while (0)
; DI void attn_unit(LAS unsigned char* lds, int wid, int b, int h, int qb) {
;     ...
;             const float mnew = fmaxf(mrow, mx), alpha = __builtin_amdgcn_exp2f(mrow - mnew); mrow = mnew;
;             float ls = 0.f;
; #pragma unroll
;             for (int i = 0; i < 16; ++i) { s0[i] = __builtin_amdgcn_exp2f(s0[i] - mnew); s1[i] = __builtin_amdgcn_exp2f(s1[i] - mnew); ls += s0[i] + s1[i]; }
;             lrow = lrow * alpha + ls;
;             if (__builtin_amdgcn_ballot_w64(alpha != 1.f) != 0ull) {
; #pragma unroll
;                 for (int dt = 0; dt < 4; ++dt)
; #pragma unroll
;                     for (int i = 0; i < 16; ++i) o[dt][i] *= alpha;
;             }
;             bf16x8 pf[4];
; #pragma unroll
;             for (int jj = 0; jj < 2; ++jj) { u32x4 w0, w1;
;                 w0.x = pk2(s0[8 * jj + 0], s0[8 * jj + 1]); w0.y = pk2(s0[8 * jj + 2], s0[8 * jj + 3]); w0.z = pk2(s0[8 * jj + 4], s0[8 * jj + 5]); w0.w = pk2(s0[8 * jj + 6], s0[8 * jj + 7]);
;                 w1.x = pk2(s1[8 * jj + 0], s1[8 * jj + 1]); w1.y = pk2(s1[8 * jj + 2], s1[8 * jj + 3]); w1.z = pk2(s1[8 * jj + 4], s1[8 * jj + 5]); w1.w = pk2(s1[8 * jj + 6], s1[8 * jj + 7]);
;                 pf[jj] = __builtin_bit_cast(bf16x8, w0); pf[2 + jj] = __builtin_bit_cast(bf16x8, w1); }
; #pragma unroll
;             for (int j = 0; j < 4; ++j) {
;                 if (j < 3) {
; #pragma unroll
;                     for (int dt = 0; dt < 4; ++dt) VLD(vf[(j + 1) & 1][dt], j + 1, dt);
;                 }
; #pragma unroll
;                 for (int dt = 0; dt < 4; ++dt) o[dt] = __builtin_amdgcn_mfma_f32_32x32x16_bf16(__builtin_bit_cast(bf16x8, vf[j & 1][dt]), pf[j], o[dt], 0, 0, 0);
;                 __builtin_amdgcn_sched_barrier(0); }
.LBB0_1073:
	s_cmp_lt_i32 s34, 10
	s_cselect_b64 s[2:3], -1, 0
	s_and_b64 s[2:3], s[2:3], s[4:5]
	s_andn2_b64 vcc, exec, s[2:3]
	s_cbranch_vccnz .LBB0_1101
	s_mov_b64 s[4:5], s[0:1]
	s_cmpk_gt_i32 s6, 0xff
	s_cbranch_scc1 .LBB0_1101
	s_mul_i32 s4, s33, 0x2200
	s_and_b32 s28, s88, 0xffffffc0
	s_lshl_b32 s29, s33, 5
	s_mov_b32 s5, 0
	s_add_i32 s30, s4, 0
	s_lshl_b32 s31, s6, 2
	s_lshl_b32 s36, s7, 2
	s_movk_i32 s37, 0x1800
	v_mov_b32_e32 v200, 0x1800
	s_mov_b64 s[8:9], 0xe100000
	s_mov_b32 s38, 0xe100000
	s_waitcnt lgkmcnt(0)
	v_mov_b32_e32 v1, 0
	s_movk_i32 s39, 0x190
	s_mov_b32 s40, 0x11100000
	s_mov_b32 s41, 0x11120000
	s_mov_b32 s42, 0xe000000
	s_mov_b32 s43, 0x13100000
	s_mov_b32 s44, 0x13200000
	s_movk_i32 s45, 0xff00
	s_mov_b64 s[10:11], 0x80
	s_mov_b64 s[12:13], 0x2000
	s_mov_b64 s[14:15], 0x40000
	s_movk_i32 s46, 0x110
	s_mov_b32 s47, 0x15100000
	s_mov_b32 s48, 0x15104000
	s_mov_b32 s49, 0x15108000
	s_mov_b32 s50, 0x1510c000
	s_mov_b32 s51, 0x15110000
	s_mov_b32 s52, 0x15114000
	s_mov_b32 s53, 0x15118000
	s_mov_b32 s54, 0x1511c000
	v_mbcnt_hi_u32_b32 v201, -1, v254
	v_and_b32_e32 v216, 1, v201
	v_lshlrev_b32_e32 v216, 3, v216
	s_mov_b32 s55, s6
	s_branch .LBB0_1078
.LBB0_1076:
	v_sub_f32_e32 v80, v80, v118
	v_sub_f32_e32 v96, v96, v118
	v_exp_f32_e32 v80, v80
	v_exp_f32_e32 v96, v96
	v_sub_f32_e32 v81, v81, v118
	v_sub_f32_e32 v97, v97, v118
	v_exp_f32_e32 v81, v81
	v_exp_f32_e32 v97, v97
	v_sub_f32_e32 v82, v82, v118
	v_sub_f32_e32 v98, v98, v118
	v_exp_f32_e32 v82, v82
	v_exp_f32_e32 v98, v98
	v_sub_f32_e32 v83, v83, v118
	v_sub_f32_e32 v99, v99, v118
	v_exp_f32_e32 v83, v83
	v_exp_f32_e32 v99, v99
	v_sub_f32_e32 v84, v84, v118
	v_sub_f32_e32 v100, v100, v118
	v_add_f32_e32 v119, v96, v80
	v_exp_f32_e32 v84, v84
	v_exp_f32_e32 v100, v100
	v_sub_f32_e32 v85, v85, v118
	v_sub_f32_e32 v101, v101, v118
	v_add_f32_e32 v119, 0, v119
	v_add_f32_e32 v120, v97, v81
	v_exp_f32_e32 v85, v85
	v_exp_f32_e32 v101, v101
	v_sub_f32_e32 v86, v86, v118
	v_sub_f32_e32 v102, v102, v118
	v_add_f32_e32 v119, v120, v119
	v_add_f32_e32 v120, v98, v82
	v_exp_f32_e32 v86, v86
	v_exp_f32_e32 v102, v102
	v_sub_f32_e32 v87, v87, v118
	v_sub_f32_e32 v103, v103, v118
	v_add_f32_e32 v119, v120, v119
	v_add_f32_e32 v120, v99, v83
	v_exp_f32_e32 v87, v87
	v_exp_f32_e32 v103, v103
	v_sub_f32_e32 v88, v88, v118
	v_sub_f32_e32 v104, v104, v118
	v_add_f32_e32 v119, v120, v119
	v_add_f32_e32 v120, v100, v84
	v_exp_f32_e32 v88, v88
	v_exp_f32_e32 v104, v104
	v_sub_f32_e32 v89, v89, v118
	v_sub_f32_e32 v105, v105, v118
	v_add_f32_e32 v119, v120, v119
	v_add_f32_e32 v120, v101, v85
	v_exp_f32_e32 v89, v89
	v_exp_f32_e32 v105, v105
	v_sub_f32_e32 v90, v90, v118
	v_sub_f32_e32 v106, v106, v118
	v_add_f32_e32 v119, v120, v119
	v_add_f32_e32 v120, v102, v86
	v_exp_f32_e32 v90, v90
	v_exp_f32_e32 v106, v106
	v_sub_f32_e32 v91, v91, v118
	v_sub_f32_e32 v107, v107, v118
	v_add_f32_e32 v119, v120, v119
	v_add_f32_e32 v120, v103, v87
	v_exp_f32_e32 v91, v91
	v_exp_f32_e32 v107, v107
	v_sub_f32_e32 v92, v92, v118
	v_sub_f32_e32 v108, v108, v118
	v_add_f32_e32 v119, v120, v119
	v_add_f32_e32 v120, v104, v88
	v_exp_f32_e32 v92, v92
	v_exp_f32_e32 v108, v108
	v_sub_f32_e32 v93, v93, v118
	v_sub_f32_e32 v109, v109, v118
	v_add_f32_e32 v119, v120, v119
	v_add_f32_e32 v120, v105, v89
	v_exp_f32_e32 v93, v93
	v_exp_f32_e32 v109, v109
	v_sub_f32_e32 v94, v94, v118
	v_sub_f32_e32 v110, v110, v118
	v_add_f32_e32 v119, v120, v119
	v_add_f32_e32 v120, v106, v90
	v_exp_f32_e32 v94, v94
	v_exp_f32_e32 v110, v110
	v_sub_f32_e32 v95, v95, v118
	v_sub_f32_e32 v111, v111, v118
	v_add_f32_e32 v119, v120, v119
	v_add_f32_e32 v120, v107, v91
	v_exp_f32_e32 v95, v95
	v_exp_f32_e32 v111, v111
	v_add_f32_e32 v119, v120, v119
	v_add_f32_e32 v120, v108, v92
	v_add_f32_e32 v119, v120, v119
	v_add_f32_e32 v120, v109, v93
	v_cvt_pk_bf16_f32 v80, v80, v81
	v_cvt_pk_bf16_f32 v81, v82, v83
	v_cvt_pk_bf16_f32 v82, v84, v85
	v_cvt_pk_bf16_f32 v83, v86, v87
	v_add_f32_e32 v119, v120, v119
	v_cvt_pk_bf16_f32 v86, v92, v93
	v_mfma_f32_32x32x16_bf16 v[64:79], v[2:5], v[80:83], v[64:79]
	v_add_f32_e32 v2, v110, v94
	v_add_f32_e32 v2, v2, v119
	v_add_f32_e32 v3, v111, v95
	v_add_f32_e32 v118, v3, v2
	v_cvt_pk_bf16_f32 v2, v96, v97
	v_cvt_pk_bf16_f32 v3, v98, v99
	v_cvt_pk_bf16_f32 v4, v100, v101
	s_waitcnt lgkmcnt(1)
	v_mfma_f32_32x32x16_bf16 v[48:63], v[112:115], v[80:83], v[48:63]
	v_cvt_pk_bf16_f32 v5, v102, v103
	v_cvt_pk_bf16_f32 v87, v94, v95
	v_fmac_f32_e32 v118, v185, v0
	v_cvt_pk_bf16_f32 v84, v88, v89
	v_cvt_pk_bf16_f32 v85, v90, v91
	v_cvt_pk_bf16_f32 v88, v104, v105
	v_cvt_pk_bf16_f32 v89, v106, v107
	v_mfma_f32_32x32x16_bf16 v[32:47], v[10:13], v[80:83], v[32:47]
	ds_read_b128 v[10:13], v15 offset:1056
	ds_read_b128 v[92:95], v116 offset:1568
	ds_read_b128 v[96:99], v117 offset:2080
	ds_read_b128 v[100:103], v14 offset:2592
	v_cvt_pk_bf16_f32 v90, v108, v109
	v_cvt_pk_bf16_f32 v91, v110, v111
	s_waitcnt lgkmcnt(4)
	v_mfma_f32_32x32x16_bf16 v[16:31], v[6:9], v[80:83], v[16:31]
	s_waitcnt lgkmcnt(3)
	v_mfma_f32_32x32x16_bf16 v[64:79], v[10:13], v[84:87], v[64:79]
	s_waitcnt lgkmcnt(2)
	v_mfma_f32_32x32x16_bf16 v[48:63], v[92:95], v[84:87], v[48:63]
	ds_read_b128 v[6:9], v15 offset:1088
	ds_read_b128 v[10:13], v116 offset:1600
	ds_read_b128 v[80:83], v117 offset:2112
	ds_read_b128 v[92:95], v14 offset:2624
	s_waitcnt lgkmcnt(5)
	v_mfma_f32_32x32x16_bf16 v[32:47], v[96:99], v[84:87], v[32:47]
	s_waitcnt lgkmcnt(4)
	v_mfma_f32_32x32x16_bf16 v[16:31], v[100:103], v[84:87], v[16:31]
	s_waitcnt lgkmcnt(3)
	v_mfma_f32_32x32x16_bf16 v[64:79], v[6:9], v[2:5], v[64:79]
	s_waitcnt lgkmcnt(2)
	v_mfma_f32_32x32x16_bf16 v[48:63], v[10:13], v[2:5], v[48:63]
	s_waitcnt lgkmcnt(1)
	v_mfma_f32_32x32x16_bf16 v[32:47], v[80:83], v[2:5], v[32:47]
	ds_read_b128 v[6:9], v15 offset:1120
	ds_read_b128 v[10:13], v116 offset:1632
	ds_read_b128 v[80:83], v117 offset:2144
	ds_read_b128 v[84:87], v14 offset:2656
	s_waitcnt lgkmcnt(4)
	v_mfma_f32_32x32x16_bf16 v[16:31], v[92:95], v[2:5], v[16:31]
	s_waitcnt lgkmcnt(3)
	v_mfma_f32_32x32x16_bf16 v[64:79], v[6:9], v[88:91], v[64:79]
	s_waitcnt lgkmcnt(2)
	v_mfma_f32_32x32x16_bf16 v[48:63], v[10:13], v[88:91], v[48:63]
	s_waitcnt lgkmcnt(1)
	v_mfma_f32_32x32x16_bf16 v[32:47], v[80:83], v[88:91], v[32:47]
	s_waitcnt lgkmcnt(0)
	v_mfma_f32_32x32x16_bf16 v[16:31], v[84:87], v[88:91], v[16:31]
	v_mov_b32_e32 v185, v118
; #define LAS __attribute__((address_space(3)))
; DI u32x2 pk4(f32x4 v) { u32x2 r; r.x = pk2(v[0], v[1]); r.y = pk2(v[2], v[3]); return r; }
; DI float shfl_xor_l(float v, int lane, int m) { return __int_as_float(__builtin_amdgcn_ds_bpermute((lane ^ m) << 2, __float_as_int(v))); }
; DI void attn_unit(LAS unsigned char* lds, int wid, int b, int h, int qb) {
;     ...
;     const float lt = lrow + shfl_xor_l(lrow, lane, 32), inv = 1.f / lt;
;     LAS unsigned char* pt_ = lds + ABUF + wid * (32 * 272);
; #pragma unroll
;     for (int dt = 0; dt < 4; ++dt)
; #pragma unroll
;         for (int blk = 0; blk < 4; ++blk) { const f32x4 v = {o[dt][4 * blk] * inv, o[dt][4 * blk + 1] * inv, o[dt][4 * blk + 2] * inv, o[dt][4 * blk + 3] * inv};
;             *(LAS u32x2*)(pt_ + n * 272 + (32 * dt + 8 * blk + 4 * g) * 2) = pk4(v); }
;     asm volatile("" ::: "memory");
;     bf16_t* od = WSB(OFF_O) + ((size_t)b * SEQ + q0 + (lane >> 4)) * 2048 + h * 128 + (lane & 15) * 8;
; #pragma unroll
;     for (int j = 0; j < 8; ++j) { const u32x4 w = *(const LAS u32x4*)(pt_ + (4 * j + (lane >> 4)) * 272 + (lane & 15) * 16); *(u32x4*)(od + (size_t)(4 * j) * 2048) = w; }
;     asm volatile("" ::: "memory");
.LBB0_1077:
	ds_bpermute_b32 v0, v189, v185
	s_waitcnt lgkmcnt(0)
	s_barrier
	s_mov_b32 s25, s5
	v_add_f32_e32 v0, v185, v0
	v_div_scale_f32 v2, s[18:19], v0, v0, 1.0
	v_rcp_f32_e32 v3, v2
	v_div_scale_f32 v4, vcc, 1.0, v0, 1.0
	s_add_i32 s55, s55, s7
	v_fma_f32 v5, -v2, v3, 1.0
	v_fmac_f32_e32 v3, v5, v3
	v_mul_f32_e32 v5, v4, v3
	v_fma_f32 v6, -v2, v5, v4
	v_fmac_f32_e32 v5, v6, v3
	v_fma_f32 v2, -v2, v5, v4
	v_div_fmas_f32 v2, v2, v3, v5
	v_div_fixup_f32 v0, v2, v0, 1.0
	v_mul_u32_u24_e32 v2, 0x110, v202
	v_add3_u32 v8, s30, v2, v188
	v_pk_mul_f32 v[2:3], v[64:65], v[0:1] op_sel_hi:[1,0]
	v_pk_mul_f32 v[4:5], v[66:67], v[0:1] op_sel_hi:[1,0]
	v_cvt_pk_bf16_f32 v2, v2, v3
	v_cvt_pk_bf16_f32 v3, v4, v5
	v_pk_mul_f32 v[4:5], v[68:69], v[0:1] op_sel_hi:[1,0]
	v_pk_mul_f32 v[6:7], v[70:71], v[0:1] op_sel_hi:[1,0]
	v_cvt_pk_bf16_f32 v4, v4, v5
	v_cvt_pk_bf16_f32 v5, v6, v7
	v_add_u32_e32 v8, 0xac00, v8
	ds_write2_b64 v8, v[2:3], v[4:5] offset1:2
	v_pk_mul_f32 v[2:3], v[72:73], v[0:1] op_sel_hi:[1,0]
	v_pk_mul_f32 v[4:5], v[74:75], v[0:1] op_sel_hi:[1,0]
	v_cvt_pk_bf16_f32 v2, v2, v3
	v_cvt_pk_bf16_f32 v3, v4, v5
	v_pk_mul_f32 v[4:5], v[76:77], v[0:1] op_sel_hi:[1,0]
	v_pk_mul_f32 v[6:7], v[78:79], v[0:1] op_sel_hi:[1,0]
	v_cvt_pk_bf16_f32 v4, v4, v5
	v_cvt_pk_bf16_f32 v5, v6, v7
	ds_write2_b64 v8, v[2:3], v[4:5] offset0:4 offset1:6
	v_pk_mul_f32 v[2:3], v[48:49], v[0:1] op_sel_hi:[1,0]
	v_pk_mul_f32 v[4:5], v[50:51], v[0:1] op_sel_hi:[1,0]
	v_cvt_pk_bf16_f32 v2, v2, v3
	v_cvt_pk_bf16_f32 v3, v4, v5
	v_pk_mul_f32 v[4:5], v[52:53], v[0:1] op_sel_hi:[1,0]
	v_pk_mul_f32 v[6:7], v[54:55], v[0:1] op_sel_hi:[1,0]
	v_cvt_pk_bf16_f32 v4, v4, v5
	v_cvt_pk_bf16_f32 v5, v6, v7
	ds_write2_b64 v8, v[2:3], v[4:5] offset0:8 offset1:10
	v_pk_mul_f32 v[2:3], v[56:57], v[0:1] op_sel_hi:[1,0]
	v_pk_mul_f32 v[4:5], v[58:59], v[0:1] op_sel_hi:[1,0]
	v_cvt_pk_bf16_f32 v2, v2, v3
	v_cvt_pk_bf16_f32 v3, v4, v5
	v_pk_mul_f32 v[4:5], v[60:61], v[0:1] op_sel_hi:[1,0]
	v_pk_mul_f32 v[6:7], v[62:63], v[0:1] op_sel_hi:[1,0]
	v_cvt_pk_bf16_f32 v4, v4, v5
	v_cvt_pk_bf16_f32 v5, v6, v7
	ds_write2_b64 v8, v[2:3], v[4:5] offset0:12 offset1:14
	v_pk_mul_f32 v[2:3], v[32:33], v[0:1] op_sel_hi:[1,0]
	v_pk_mul_f32 v[4:5], v[34:35], v[0:1] op_sel_hi:[1,0]
	v_cvt_pk_bf16_f32 v2, v2, v3
	v_cvt_pk_bf16_f32 v3, v4, v5
	v_pk_mul_f32 v[4:5], v[36:37], v[0:1] op_sel_hi:[1,0]
	v_pk_mul_f32 v[6:7], v[38:39], v[0:1] op_sel_hi:[1,0]
	v_cvt_pk_bf16_f32 v4, v4, v5
	v_cvt_pk_bf16_f32 v5, v6, v7
	ds_write2_b64 v8, v[2:3], v[4:5] offset0:16 offset1:18
	v_pk_mul_f32 v[2:3], v[40:41], v[0:1] op_sel_hi:[1,0]
	v_pk_mul_f32 v[4:5], v[42:43], v[0:1] op_sel_hi:[1,0]
	v_cvt_pk_bf16_f32 v2, v2, v3
	v_cvt_pk_bf16_f32 v3, v4, v5
	v_pk_mul_f32 v[4:5], v[44:45], v[0:1] op_sel_hi:[1,0]
	v_pk_mul_f32 v[6:7], v[46:47], v[0:1] op_sel_hi:[1,0]
	v_cvt_pk_bf16_f32 v4, v4, v5
	v_cvt_pk_bf16_f32 v5, v6, v7
	ds_write2_b64 v8, v[2:3], v[4:5] offset0:20 offset1:22
	v_pk_mul_f32 v[2:3], v[16:17], v[0:1] op_sel_hi:[1,0]
	v_pk_mul_f32 v[4:5], v[18:19], v[0:1] op_sel_hi:[1,0]
	v_cvt_pk_bf16_f32 v2, v2, v3
	v_cvt_pk_bf16_f32 v3, v4, v5
	v_pk_mul_f32 v[4:5], v[20:21], v[0:1] op_sel_hi:[1,0]
	v_pk_mul_f32 v[6:7], v[22:23], v[0:1] op_sel_hi:[1,0]
	v_cvt_pk_bf16_f32 v4, v4, v5
	v_cvt_pk_bf16_f32 v5, v6, v7
	ds_write2_b64 v8, v[2:3], v[4:5] offset0:24 offset1:26
	v_pk_mul_f32 v[2:3], v[24:25], v[0:1] op_sel_hi:[1,0]
	v_pk_mul_f32 v[4:5], v[26:27], v[0:1] op_sel_hi:[1,0]
	v_cvt_pk_bf16_f32 v2, v2, v3
	v_cvt_pk_bf16_f32 v3, v4, v5
	v_pk_mul_f32 v[4:5], v[28:29], v[0:1] op_sel_hi:[1,0]
	v_pk_mul_f32 v[6:7], v[30:31], v[0:1] op_sel_hi:[1,0]
	v_cvt_pk_bf16_f32 v4, v4, v5
	v_cvt_pk_bf16_f32 v5, v6, v7
	ds_write2_b64 v8, v[2:3], v[4:5] offset0:28 offset1:30
	v_ashrrev_i32_e32 v2, 4, v187
	v_ashrrev_i32_e32 v3, 31, v2
	v_lshl_add_u64 v[4:5], s[16:17], 0, v[2:3]
	v_lshlrev_b64 v[4:5], 12, v[4:5]
	v_lshl_add_u64 v[4:5], s[26:27], 0, v[4:5]
	v_lshl_add_u64 v[4:5], v[4:5], 0, s[24:25]
	v_lshlrev_b32_e32 v0, 1, v186
	v_lshl_add_u64 v[10:11], v[4:5], 0, v[0:1]
	v_mul_lo_u32 v0, v2, s46
	v_add3_u32 v0, s30, v184, v0
	ds_read_b128 v[2:5], v0 offset:44032
	ds_read_b128 v[6:9], v0 offset:45120
	v_add_co_u32_e32 v12, vcc, s47, v10
	s_add_i32 s31, s31, s36
	s_nop 0
	v_addc_co_u32_e32 v13, vcc, 0, v11, vcc
	s_waitcnt lgkmcnt(1)
	global_store_dwordx4 v[12:13], v[2:5], off
	s_cmpk_gt_i32 s55, 0xff
	s_nop 0
	v_add_co_u32_e32 v2, vcc, s48, v10
	s_nop 1
	v_addc_co_u32_e32 v3, vcc, 0, v11, vcc
	s_waitcnt lgkmcnt(0)
	global_store_dwordx4 v[2:3], v[6:9], off
	ds_read_b128 v[2:5], v0 offset:46208
	ds_read_b128 v[6:9], v0 offset:47296
	v_add_co_u32_e32 v12, vcc, s49, v10
	s_nop 1
	v_addc_co_u32_e32 v13, vcc, 0, v11, vcc
	s_waitcnt lgkmcnt(1)
	global_store_dwordx4 v[12:13], v[2:5], off
	s_nop 1
	v_add_co_u32_e32 v2, vcc, s50, v10
	s_nop 1
	v_addc_co_u32_e32 v3, vcc, 0, v11, vcc
	s_waitcnt lgkmcnt(0)
	global_store_dwordx4 v[2:3], v[6:9], off
	ds_read_b128 v[2:5], v0 offset:48384
	ds_read_b128 v[6:9], v0 offset:49472
	v_add_co_u32_e32 v12, vcc, s51, v10
	s_nop 1
	v_addc_co_u32_e32 v13, vcc, 0, v11, vcc
	s_waitcnt lgkmcnt(1)
	global_store_dwordx4 v[12:13], v[2:5], off
	s_nop 1
	v_add_co_u32_e32 v2, vcc, s52, v10
	s_nop 1
	v_addc_co_u32_e32 v3, vcc, 0, v11, vcc
	s_waitcnt lgkmcnt(0)
	global_store_dwordx4 v[2:3], v[6:9], off
	ds_read_b128 v[2:5], v0 offset:50560
	ds_read_b128 v[6:9], v0 offset:51648
	v_add_co_u32_e32 v12, vcc, 0x15118000, v10
	s_nop 1
	v_addc_co_u32_e32 v13, vcc, 0, v11, vcc
	s_waitcnt lgkmcnt(1)
	global_store_dwordx4 v[12:13], v[2:5], off
	s_nop 1
	v_add_co_u32_e32 v2, vcc, 0x1511c000, v10
	s_nop 1
	v_addc_co_u32_e32 v3, vcc, 0, v11, vcc
	s_waitcnt lgkmcnt(0)
	global_store_dwordx4 v[2:3], v[6:9], off
	s_cbranch_scc1 .LBB0_1101
; DI int lane_id() { int l = __builtin_amdgcn_mbcnt_hi(-1, __builtin_amdgcn_mbcnt_lo(-1, 0)); asm volatile("" : "+v"(l)); return l; }
; #define A_LOAD(kt) do { const size_t ko = (size_t)(kt) * 64; st0 = *(const u32x4*)(kn_src + ko * 2048); st1 = *(const u32x4*)(kn_src + (ko + 32) * 2048); \
;         st2 = *(const u32x4*)(kr_src + ko * 64); st3 = *(const u32x4*)(v_src + ko); st4 = *(const u32x4*)(v_src + ko + (size_t)64 * 8192); } while (0)
; DI void attn_unit(LAS unsigned char* lds, int wid, int b, int h, int qb) {
;     ...
;     const int lane = lane_id(), tid = wid * 64 + lane, n = lane & 31, g = lane >> 5;
;     const int q0 = qb * 256 + wid * 32, cq = q0 >> 6, nkt = 4 * qb + 4;
;     const size_t tokq = (size_t)b * SEQ + q0 + n;
;     const bf16_t* Q = WSB(OFF_Q); const bf16_t* KN = WSB(OFF_KN); const bf16_t* KR = WSB(OFF_KR); const bf16_t* VT = WSB(OFF_VT2);
;     bf16x8 qf[12];
; #pragma unroll
;     for (int ks = 0; ks < 12; ++ks) qf[ks] = *(const bf16x8*)(Q + tokq * 3072 + h * 192 + ks * 16 + g * 8);
;     f32x16 o[4];
; #pragma unroll
;     for (int dt = 0; dt < 4; ++dt)
; #pragma unroll
;         for (int i = 0; i < 16; ++i) o[dt][i] = 0.f;
;     float mrow = -__builtin_inff(), lrow = 0.f;
;     const int krow = tid >> 4, kc16 = tid & 15, rrow = tid >> 3, rc8 = tid & 7;
;     const bf16_t* kn_src = KN + ((size_t)b * SEQ + krow) * 2048 + h * 128 + kc16 * 8;
;     const bf16_t* kr_src = KR + ((size_t)b * SEQ + rrow) * 64 + rc8 * 8;
;     const bf16_t* v_src = VT + ((size_t)h * 128 + rrow) * 8192 + (size_t)b * SEQ + rc8 * 8;
;     const int kn_dst = krow * KROW + kc16 * 16, kr_dst = rrow * KROW + 256 + rc8 * 16, v_dst = KBYTES + rrow * VROW + rc8 * 16;
;     u32x4 st0, st1, st2, st3, st4;
;     ...
;     A_LOAD(0); A_WRITE(0); __syncthreads();
.LBB0_1078:
	s_lshl_b32 s4, s55, 2
	s_and_b32 s4, s4, 28
	s_ashr_i32 s59, s55, 6
	s_mov_b64 s[16:17], s[0:1]
	v_mov_b32_e32 v183, v201
	s_add_i32 s4, s4, s59
	s_bfe_u32 s56, s55, 0x30003
	s_load_dwordx2 s[24:25], s[16:17], 0xa8
	s_ashr_i32 s22, s4, 4
	s_and_b32 s20, s4, 15
	s_xor_b32 s4, s56, 15
	s_lshl_b32 s18, s4, 8
	s_ashr_i32 s23, s22, 31
	s_lshr_b32 s57, s55, 3
	s_add_i32 s21, s18, s29
	s_lshl_b32 s61, s4, 2
	s_lshl_b64 s[16:17], s[22:23], 12
	v_and_b32_e32 v197, 31, v183
	s_add_u32 s26, s16, s21
	v_or_b32_e32 v0, s26, v197
	s_waitcnt lgkmcnt(0)
	v_mov_b64_e32 v[2:3], s[24:25]
	v_mad_u64_u32 v[2:3], s[18:19], v0, s37, v[2:3]
	v_add_u32_e32 v0, s28, v183
	v_ashrrev_i32_e32 v26, 3, v0
	v_ashrrev_i32_e32 v27, 31, v26
	s_addc_u32 s27, s17, 0
	s_mul_i32 s58, s20, 0xc0
	v_ashrrev_i32_e32 v24, 4, v0
	v_lshl_add_u64 v[4:5], s[16:17], 0, v[26:27]
	v_mad_i32_i24 v3, s27, v200, v3
	s_lshl_b32 s4, s58, 1
	v_ashrrev_i32_e32 v25, 31, v24
	v_lshlrev_b64 v[4:5], 7, v[4:5]
	v_lshlrev_b32_e32 v6, 4, v183
	v_lshl_add_u64 v[22:23], v[2:3], 0, s[4:5]
	v_lshl_add_u64 v[2:3], s[16:17], 0, v[24:25]
	s_lshl_b32 s4, s20, 7
	v_lshl_add_u64 v[4:5], s[24:25], 0, v[4:5]
	v_and_b32_e32 v28, 0x70, v6
	v_mov_b32_e32 v29, v1
	v_lshlrev_b64 v[2:3], 12, v[2:3]
	v_lshl_add_u64 v[10:11], v[4:5], 0, v[28:29]
	v_lshl_add_u64 v[4:5], v[26:27], 0, s[4:5]
	v_and_b32_e32 v32, 15, v183
	v_lshl_add_u64 v[2:3], s[24:25], 0, v[2:3]
	s_lshl_b32 s18, s20, 8
	s_mov_b32 s19, s5
	v_lshlrev_b64 v[4:5], 14, v[4:5]
	v_lshl_add_u64 v[2:3], v[2:3], 0, s[18:19]
	v_lshlrev_b32_e32 v0, 4, v32
	v_lshl_add_u64 v[4:5], s[24:25], 0, v[4:5]
	s_lshl_b64 s[18:19], s[22:23], 13
	v_lshl_add_u64 v[2:3], v[2:3], 0, v[0:1]
	v_lshl_add_u64 v[4:5], v[4:5], 0, s[18:19]
	v_lshl_add_u64 v[18:19], v[4:5], 0, v[28:29]
	v_add_co_u32_e32 v4, vcc, s40, v2
	v_ashrrev_i32_e32 v29, 5, v183
	s_nop 0
	v_addc_co_u32_e32 v5, vcc, 0, v3, vcc
	v_add_co_u32_e32 v6, vcc, s41, v2
	v_lshlrev_b32_e32 v184, 3, v29
	s_nop 0
	v_addc_co_u32_e32 v7, vcc, 0, v3, vcc
	v_add_co_u32_e32 v10, vcc, s42, v10
	v_ashrrev_i32_e32 v185, 31, v184
	s_nop 0
	v_addc_co_u32_e32 v11, vcc, 0, v11, vcc
	v_add_co_u32_e32 v14, vcc, s43, v18
	v_lshl_add_u64 v[22:23], v[184:185], 1, v[22:23]
	s_nop 0
	v_addc_co_u32_e32 v15, vcc, 0, v19, vcc
	v_add_co_u32_e32 v18, vcc, s44, v18
	global_load_dwordx4 v[2:5], v[4:5], off
	s_nop 0
	global_load_dwordx4 v[6:9], v[6:7], off
	v_addc_co_u32_e32 v19, vcc, 0, v19, vcc
	v_lshl_add_u64 v[30:31], v[22:23], 0, s[8:9]
	v_add_co_u32_e32 v22, vcc, s38, v22
	global_load_dwordx4 v[10:13], v[10:11], off
	s_nop 0
	v_addc_co_u32_e32 v23, vcc, 0, v23, vcc
	global_load_dwordx4 v[14:17], v[14:15], off
	s_lshr_b32 s62, s21, 6
	global_load_dwordx4 v[18:21], v[18:19], off
	s_nop 0
	global_load_dwordx4 v[138:141], v[30:31], off offset:32
	global_load_dwordx4 v[134:137], v[30:31], off offset:64
	global_load_dwordx4 v[130:133], v[30:31], off offset:96
	global_load_dwordx4 v[126:129], v[30:31], off offset:128
	global_load_dwordx4 v[122:125], v[30:31], off offset:160
	global_load_dwordx4 v[118:121], v[30:31], off offset:192
	global_load_dwordx4 v[114:117], v[30:31], off offset:224
	global_load_dwordx4 v[110:113], v[30:31], off offset:256
	global_load_dwordx4 v[106:109], v[30:31], off offset:288
	global_load_dwordx4 v[102:105], v[30:31], off offset:320
	global_load_dwordx4 v[142:145], v[22:23], off
	global_load_dwordx4 v[98:101], v[30:31], off offset:352
	v_mad_u64_u32 v[186:187], s[20:21], v24, s39, v[0:1]
	v_mad_u64_u32 v[188:189], s[20:21], v26, s39, v[28:29]
	v_add_u32_e32 v22, 0, v186
	s_and_b32 s20, s31, 12
	s_add_i32 s20, s20, s59
	s_and_b32 s60, s20, 15
	s_or_b32 s63, s61, 3
	s_waitcnt vmcnt(0)
	ds_write_b128 v22, v[2:5]
	ds_write_b128 v22, v[6:9] offset:12800
	v_add_u32_e32 v2, 0, v188
	v_mul_lo_u32 v3, v26, s45
	v_add_u32_e32 v198, v188, v3
	v_sub_u32_e32 v198, v198, v216
	s_lshl_b32 s59, s60, 21
	s_add_u32 s20, s18, s59
	ds_write_b128 v2, v[10:13] offset:256
	v_add_u32_e32 v2, v2, v3
	v_sub_u32_e32 v2, v2, v216
	v_add_u32_e32 v3, 0x6400, v2
	v_add_u32_e32 v2, 0x8800, v2
	ds_write2_b64 v3, v[14:15], v[16:17] offset1:2
	ds_write2_b64 v2, v[18:19], v[20:21] offset1:2
	v_lshlrev_b32_e32 v2, 2, v183
	v_xor_b32_e32 v185, 0x80, v2
	v_lshlrev_b64 v[2:3], 14, v[26:27]
	s_addc_u32 s21, s19, 0
	v_lshl_add_u64 v[190:191], s[20:21], 0, v[2:3]
	s_lshl_b64 s[20:21], s[22:23], 19
	s_add_u32 s20, s20, 0xe002000
	s_addc_u32 s21, s21, 0
	v_lshlrev_b64 v[2:3], 7, v[26:27]
	v_lshl_add_u64 v[192:193], s[20:21], 0, v[2:3]
	s_lshl_b64 s[22:23], s[22:23], 24
	v_lshlrev_b64 v[2:3], 12, v[24:25]
	v_mov_b32_e32 v16, v1
	v_mov_b32_e32 v17, v1
	v_lshlrev_b32_e32 v182, 3, v32
	v_lshlrev_b32_e32 v202, 4, v29
	v_or_b32_e32 v190, v190, v28
	v_or_b32_e32 v192, v192, v28
	v_lshl_add_u64 v[194:195], s[22:23], 0, v[2:3]
	s_lshl_b32 s60, s60, 8
	v_mov_b32_e32 v2, v1
	v_mov_b32_e32 v3, v1
	v_mov_b32_e32 v4, v1
	v_mov_b32_e32 v5, v1
	v_mov_b32_e32 v6, v1
	v_mov_b32_e32 v7, v1
	v_mov_b32_e32 v8, v1
	v_mov_b32_e32 v9, v1
	v_mov_b32_e32 v10, v1
	v_mov_b32_e32 v11, v1
	v_mov_b32_e32 v12, v1
	v_mov_b32_e32 v13, v1
	v_mov_b32_e32 v14, v1
	v_mov_b32_e32 v15, v1
	v_mov_b64_e32 v[32:33], v[16:17]
	v_mov_b64_e32 v[48:49], v[16:17]
	v_mov_b64_e32 v[64:65], v[16:17]
	v_mul_u32_u24_e32 v199, 0x190, v197
	v_mul_u32_u24_e32 v189, 0x90, v197
	v_or3_b32 v194, v194, s60, v0
	v_mov_b32_e32 v170, 0xff800000
	v_mov_b64_e32 v[30:31], v[14:15]
	v_mov_b64_e32 v[28:29], v[12:13]
	v_mov_b64_e32 v[26:27], v[10:11]
	v_mov_b64_e32 v[24:25], v[8:9]
	v_mov_b64_e32 v[22:23], v[6:7]
	v_mov_b64_e32 v[20:21], v[4:5]
	v_mov_b64_e32 v[18:19], v[2:3]
	v_mov_b64_e32 v[46:47], v[14:15]
	v_mov_b64_e32 v[44:45], v[12:13]
	v_mov_b64_e32 v[42:43], v[10:11]
	v_mov_b64_e32 v[40:41], v[8:9]
	v_mov_b64_e32 v[38:39], v[6:7]
	v_mov_b64_e32 v[36:37], v[4:5]
	v_mov_b64_e32 v[34:35], v[2:3]
	v_mov_b64_e32 v[62:63], v[14:15]
	v_mov_b64_e32 v[60:61], v[12:13]
	v_mov_b64_e32 v[58:59], v[10:11]
	v_mov_b64_e32 v[56:57], v[8:9]
	v_mov_b64_e32 v[54:55], v[6:7]
	v_mov_b64_e32 v[52:53], v[4:5]
	v_mov_b64_e32 v[50:51], v[2:3]
	v_mov_b32_e32 v187, 0
	s_mov_b32 s64, s5
	s_waitcnt lgkmcnt(0)
	s_barrier
; #define LAS __attribute__((address_space(3)))
; DI float shfl_xor_l(float v, int lane, int m) { return __int_as_float(__builtin_amdgcn_ds_bpermute((lane ^ m) << 2, __float_as_int(v))); }
; #define A_LOAD(kt) do { const size_t ko = (size_t)(kt) * 64; st0 = *(const u32x4*)(kn_src + ko * 2048); st1 = *(const u32x4*)(kn_src + (ko + 32) * 2048); \
;         st2 = *(const u32x4*)(kr_src + ko * 64); st3 = *(const u32x4*)(v_src + ko); st4 = *(const u32x4*)(v_src + ko + (size_t)64 * 8192); } while (0)
; #define VLD(dst, j, dt) do { LAS unsigned char* va_ = vb + (32 * (dt) + n) * VROW + (16 * (j) + 4 * g) * 2; const u32x2 lo_ = *(const LAS u32x2*)(va_), hi_ = *(const LAS u32x2*)(va_ + 16); dst = (u32x4){lo_.x, lo_.y, hi_.x, hi_.y}; } while (0)
; DI void attn_unit(LAS unsigned char* lds, int wid, int b, int h, int qb) {
;     ...
;     for (int kt = 0; kt < nkt; ++kt) {
;         const int buf = kt & 1;
;         if (kt + 1 < nkt) A_LOAD(kt + 1);
;         if (kt <= cq) {
;             LAS unsigned char* kb = lds + buf * ABUF; LAS unsigned char* vb = kb + KBYTES;
;             f32x16 s0, s1;
; #pragma unroll
;             for (int i = 0; i < 16; ++i) { s0[i] = 0.f; s1[i] = 0.f; }
;     ...
;             bf16x8 ka[3][2];
;             ka[0][0] = KLD(0, 0); ka[0][1] = KLD(0, 1); ka[1][0] = KLD(1, 0); ka[1][1] = KLD(1, 1);
; #pragma unroll
;             for (int ks = 0; ks < 12; ++ks) {
;                 if (ks + 2 < 12) { ka[(ks + 2) % 3][0] = KLD(ks + 2, 0); ka[(ks + 2) % 3][1] = KLD(ks + 2, 1); }
;                 s0 = __builtin_amdgcn_mfma_f32_32x32x16_bf16(ka[ks % 3][0], qf[ks], s0, 0, 0, 0); s1 = __builtin_amdgcn_mfma_f32_32x32x16_bf16(ka[ks % 3][1], qf[ks], s1, 0, 0, 0);
;                 __builtin_amdgcn_sched_barrier(0); }
;             u32x4 vf[2][4];
; #pragma unroll
;             for (int dt = 0; dt < 4; ++dt) VLD(vf[0][dt], 0, dt);
;             float mx = s0[0];
; #pragma unroll
;             for (int i = 1; i < 16; ++i) mx = fmaxf(mx, s0[i]);
; #pragma unroll
;             for (int i = 0; i < 16; ++i) mx = fmaxf(mx, s1[i]);
;             mx = fmaxf(mx, shfl_xor_l(mx, lane, 32));
;             const float mnew = fmaxf(mrow, mx), alpha = __builtin_amdgcn_exp2f(mrow - mnew); mrow = mnew;
.LBB0_1079:
	v_lshl_add_u64 v[66:67], s[24:25], 0, v[194:195]
	v_add_co_u32_e32 v68, vcc, 0x11140000, v66
	s_and_b32 s65, s64, 1
	s_nop 0
	v_addc_co_u32_e32 v69, vcc, 0, v67, vcc
	v_add_co_u32_e32 v66, vcc, 0x11160000, v66
	s_cmp_gt_u32 s64, s62
	s_nop 0
	v_addc_co_u32_e32 v67, vcc, 0, v67, vcc
	global_load_dwordx4 v[146:149], v[68:69], off
	global_load_dwordx4 v[150:153], v[66:67], off
	v_lshl_add_u64 v[68:69], s[24:25], 0, v[190:191]
	v_add_co_u32_e32 v70, vcc, 0x13100000, v68
	v_lshl_add_u64 v[66:67], s[24:25], 0, v[192:193]
	s_nop 0
	v_addc_co_u32_e32 v71, vcc, 0, v69, vcc
	global_load_dwordx4 v[154:157], v[66:67], off
	global_load_dwordx4 v[158:161], v[70:71], off offset:128
	v_add_co_u32_e32 v66, vcc, 0x13200000, v68
	s_nop 1
	v_addc_co_u32_e32 v67, vcc, 0, v69, vcc
	global_load_dwordx4 v[162:165], v[66:67], off offset:128
	s_cbranch_scc1 .LBB0_1083
	s_mul_i32 s66, s65, 0xac00
	s_add_i32 s66, s66, 0
	v_add3_u32 v171, s66, v199, v202
	ds_read_b128 v[66:69], v171
	ds_read_b128 v[166:169], v171 offset:32
	ds_read_b128 v[82:85], v171 offset:12800
	ds_read_b128 v[172:175], v171 offset:64
	ds_read_b128 v[176:179], v171 offset:12832
	ds_read_b128 v[204:207], v171 offset:12864
	s_waitcnt lgkmcnt(3)
	v_mfma_f32_32x32x16_bf16 v[82:97], v[82:85], v[142:145], 0
	v_mfma_f32_32x32x16_bf16 v[66:81], v[66:69], v[142:145], 0
	v_mfma_f32_32x32x16_bf16 v[66:81], v[166:169], v[138:141], v[66:81]
	ds_read_b128 v[166:169], v171 offset:96
	ds_read_b128 v[208:211], v171 offset:12896
	s_waitcnt lgkmcnt(3)
	v_mfma_f32_32x32x16_bf16 v[82:97], v[176:179], v[138:141], v[82:97]
	v_mfma_f32_32x32x16_bf16 v[66:81], v[172:175], v[134:137], v[66:81]
	ds_read_b128 v[172:175], v171 offset:128
	ds_read_b128 v[176:179], v171 offset:12928
	s_waitcnt lgkmcnt(4)
	v_mfma_f32_32x32x16_bf16 v[82:97], v[204:207], v[134:137], v[82:97]
	s_waitcnt lgkmcnt(3)
	v_mfma_f32_32x32x16_bf16 v[66:81], v[166:169], v[130:133], v[66:81]
	ds_read_b128 v[166:169], v171 offset:160
	ds_read_b128 v[204:207], v171 offset:12960
	s_waitcnt lgkmcnt(4)
	v_mfma_f32_32x32x16_bf16 v[82:97], v[208:211], v[130:133], v[82:97]
	s_waitcnt lgkmcnt(3)
	v_mfma_f32_32x32x16_bf16 v[66:81], v[172:175], v[126:129], v[66:81]
	ds_read_b128 v[172:175], v171 offset:192
	ds_read_b128 v[208:211], v171 offset:12992
	s_waitcnt lgkmcnt(4)
	v_mfma_f32_32x32x16_bf16 v[82:97], v[176:179], v[126:129], v[82:97]
	s_waitcnt lgkmcnt(3)
	v_mfma_f32_32x32x16_bf16 v[66:81], v[166:169], v[122:125], v[66:81]
	ds_read_b128 v[166:169], v171 offset:224
	ds_read_b128 v[176:179], v171 offset:13024
	s_waitcnt lgkmcnt(4)
	v_mfma_f32_32x32x16_bf16 v[82:97], v[204:207], v[122:125], v[82:97]
	s_waitcnt lgkmcnt(3)
	v_mfma_f32_32x32x16_bf16 v[66:81], v[172:175], v[118:121], v[66:81]
	ds_read_b128 v[172:175], v171 offset:256
	ds_read_b128 v[204:207], v171 offset:13056
	s_waitcnt lgkmcnt(4)
	v_mfma_f32_32x32x16_bf16 v[82:97], v[208:211], v[118:121], v[82:97]
	s_waitcnt lgkmcnt(3)
	v_mfma_f32_32x32x16_bf16 v[66:81], v[166:169], v[114:117], v[66:81]
	ds_read_b128 v[166:169], v171 offset:288
	ds_read_b128 v[208:211], v171 offset:13088
	s_waitcnt lgkmcnt(4)
	v_mfma_f32_32x32x16_bf16 v[82:97], v[176:179], v[114:117], v[82:97]
	s_waitcnt lgkmcnt(3)
	v_mfma_f32_32x32x16_bf16 v[66:81], v[172:175], v[110:113], v[66:81]
	ds_read_b128 v[172:175], v171 offset:320
	ds_read_b128 v[176:179], v171 offset:13120
	s_waitcnt lgkmcnt(4)
	v_mfma_f32_32x32x16_bf16 v[82:97], v[204:207], v[110:113], v[82:97]
	s_waitcnt lgkmcnt(3)
	v_mfma_f32_32x32x16_bf16 v[66:81], v[166:169], v[106:109], v[66:81]
	ds_read_b128 v[166:169], v171 offset:352
	ds_read_b128 v[212:215], v171 offset:13152
	s_waitcnt lgkmcnt(4)
	v_mfma_f32_32x32x16_bf16 v[82:97], v[208:211], v[106:109], v[82:97]
	s_waitcnt lgkmcnt(3)
	v_mfma_f32_32x32x16_bf16 v[66:81], v[172:175], v[102:105], v[66:81]
	s_waitcnt lgkmcnt(2)
	v_mfma_f32_32x32x16_bf16 v[82:97], v[176:179], v[102:105], v[82:97]
	s_waitcnt lgkmcnt(1)
	v_mfma_f32_32x32x16_bf16 v[66:81], v[166:169], v[98:101], v[66:81]
	v_add_u32_e32 v171, s66, v184
	v_add_u32_e32 v171, v171, v189
	v_add_u32_e32 v171, v171, v184
	v_add_u32_e32 v204, 0x6000, v171
	v_add_u32_e32 v205, 0x7000, v171
	v_add_u32_e32 v206, 0x8000, v171
	v_add_u32_e32 v207, 0x9000, v171
	ds_read_b128 v[166:169], v204 offset:1024
	s_nop 4
	v_max_f32_e32 v172, v67, v67
	v_max_f32_e32 v173, v66, v66
	v_max_f32_e32 v172, v173, v172
	s_waitcnt lgkmcnt(1)
	v_mfma_f32_32x32x16_bf16 v[82:97], v[212:215], v[98:101], v[82:97]
	v_max3_f32 v172, v172, v68, v69
	v_max3_f32 v172, v172, v70, v71
	v_max3_f32 v172, v172, v72, v73
	v_max3_f32 v172, v172, v74, v75
	v_max3_f32 v172, v172, v76, v77
	v_max3_f32 v172, v172, v78, v79
	v_max3_f32 v172, v172, v80, v81
	s_nop 4
	v_max3_f32 v172, v172, v82, v83
	v_max3_f32 v172, v172, v84, v85
	v_max3_f32 v172, v172, v86, v87
	v_max3_f32 v172, v172, v88, v89
	v_max3_f32 v172, v172, v90, v91
	v_max3_f32 v172, v172, v92, v93
	v_max3_f32 v172, v172, v94, v95
	v_max3_f32 v172, v172, v96, v97
	ds_bpermute_b32 v173, v185, v172
	ds_read_b128 v[178:181], v205 offset:1536
	ds_read_b128 v[174:177], v206 offset:2048
	s_waitcnt lgkmcnt(2)
	v_max3_f32 v203, v170, v172, v173
	v_sub_f32_e32 v170, v170, v203
	v_exp_f32_e32 v196, v170
	ds_read_b128 v[170:173], v207 offset:2560
	v_cmp_neq_f32_e32 vcc, 1.0, v196
	s_cbranch_vccz .LBB0_1082
; DI void attn_unit(LAS unsigned char* lds, int wid, int b, int h, int qb) {
;     ...
;             if (__builtin_amdgcn_ballot_w64(alpha != 1.f) != 0ull) {
; #pragma unroll
;                 for (int dt = 0; dt < 4; ++dt)
; #pragma unroll
;                     for (int i = 0; i < 16; ++i) o[dt][i] *= alpha;
;             }
	v_pk_mul_f32 v[64:65], v[64:65], v[196:197] op_sel_hi:[1,0]
	v_pk_mul_f32 v[62:63], v[62:63], v[196:197] op_sel_hi:[1,0]
	v_pk_mul_f32 v[60:61], v[60:61], v[196:197] op_sel_hi:[1,0]
	v_pk_mul_f32 v[58:59], v[58:59], v[196:197] op_sel_hi:[1,0]
	v_pk_mul_f32 v[56:57], v[56:57], v[196:197] op_sel_hi:[1,0]
	v_pk_mul_f32 v[54:55], v[54:55], v[196:197] op_sel_hi:[1,0]
	v_pk_mul_f32 v[52:53], v[52:53], v[196:197] op_sel_hi:[1,0]
	v_pk_mul_f32 v[50:51], v[50:51], v[196:197] op_sel_hi:[1,0]
	v_pk_mul_f32 v[48:49], v[48:49], v[196:197] op_sel_hi:[1,0]
	v_pk_mul_f32 v[46:47], v[46:47], v[196:197] op_sel_hi:[1,0]
	v_pk_mul_f32 v[44:45], v[44:45], v[196:197] op_sel_hi:[1,0]
	v_pk_mul_f32 v[42:43], v[42:43], v[196:197] op_sel_hi:[1,0]
	v_pk_mul_f32 v[40:41], v[40:41], v[196:197] op_sel_hi:[1,0]
	v_pk_mul_f32 v[38:39], v[38:39], v[196:197] op_sel_hi:[1,0]
	v_pk_mul_f32 v[36:37], v[36:37], v[196:197] op_sel_hi:[1,0]
	v_pk_mul_f32 v[34:35], v[34:35], v[196:197] op_sel_hi:[1,0]
	v_pk_mul_f32 v[32:33], v[32:33], v[196:197] op_sel_hi:[1,0]
	v_pk_mul_f32 v[30:31], v[30:31], v[196:197] op_sel_hi:[1,0]
	v_pk_mul_f32 v[28:29], v[28:29], v[196:197] op_sel_hi:[1,0]
	v_pk_mul_f32 v[26:27], v[26:27], v[196:197] op_sel_hi:[1,0]
	v_pk_mul_f32 v[24:25], v[24:25], v[196:197] op_sel_hi:[1,0]
	v_pk_mul_f32 v[22:23], v[22:23], v[196:197] op_sel_hi:[1,0]
	v_pk_mul_f32 v[20:21], v[20:21], v[196:197] op_sel_hi:[1,0]
	v_pk_mul_f32 v[18:19], v[18:19], v[196:197] op_sel_hi:[1,0]
	v_pk_mul_f32 v[16:17], v[16:17], v[196:197] op_sel_hi:[1,0]
	v_pk_mul_f32 v[14:15], v[14:15], v[196:197] op_sel_hi:[1,0]
	v_pk_mul_f32 v[12:13], v[12:13], v[196:197] op_sel_hi:[1,0]
	v_pk_mul_f32 v[10:11], v[10:11], v[196:197] op_sel_hi:[1,0]
	v_pk_mul_f32 v[8:9], v[8:9], v[196:197] op_sel_hi:[1,0]
	v_pk_mul_f32 v[6:7], v[6:7], v[196:197] op_sel_hi:[1,0]
	v_pk_mul_f32 v[4:5], v[4:5], v[196:197] op_sel_hi:[1,0]
	v_pk_mul_f32 v[2:3], v[2:3], v[196:197] op_sel_hi:[1,0]
; DI unsigned pk2(float a, float b) { f32x2 f = {a, b}; bf16v2 r = __builtin_convertvector(f, bf16v2); return __builtin_bit_cast(unsigned, r); }
; #define VLD(dst, j, dt) do { LAS unsigned char* va_ = vb + (32 * (dt) + n) * VROW + (16 * (j) + 4 * g) * 2; const u32x2 lo_ = *(const LAS u32x2*)(va_), hi_ = *(const LAS u32x2*)(va_ + 16); dst = (u32x4){lo_.x, lo_.y, hi_.x, hi_.y}; } while (0)
; DI void attn_unit(LAS unsigned char* lds, int wid, int b, int h, int qb) {
;     ...
;             float ls = 0.f;
; #pragma unroll
;             for (int i = 0; i < 16; ++i) { s0[i] = __builtin_amdgcn_exp2f(s0[i] - mnew); s1[i] = __builtin_amdgcn_exp2f(s1[i] - mnew); ls += s0[i] + s1[i]; }
;             lrow = lrow * alpha + ls;
;             if (__builtin_amdgcn_ballot_w64(alpha != 1.f) != 0ull) {
; #pragma unroll
;                 for (int dt = 0; dt < 4; ++dt)
; #pragma unroll
;                     for (int i = 0; i < 16; ++i) o[dt][i] *= alpha;
;             }
;             bf16x8 pf[4];
; #pragma unroll
;             for (int jj = 0; jj < 2; ++jj) { u32x4 w0, w1;
;                 w0.x = pk2(s0[8 * jj + 0], s0[8 * jj + 1]); w0.y = pk2(s0[8 * jj + 2], s0[8 * jj + 3]); w0.z = pk2(s0[8 * jj + 4], s0[8 * jj + 5]); w0.w = pk2(s0[8 * jj + 6], s0[8 * jj + 7]);
;                 w1.x = pk2(s1[8 * jj + 0], s1[8 * jj + 1]); w1.y = pk2(s1[8 * jj + 2], s1[8 * jj + 3]); w1.z = pk2(s1[8 * jj + 4], s1[8 * jj + 5]); w1.w = pk2(s1[8 * jj + 6], s1[8 * jj + 7]);
;                 pf[jj] = __builtin_bit_cast(bf16x8, w0); pf[2 + jj] = __builtin_bit_cast(bf16x8, w1); }
; #pragma unroll
;             for (int j = 0; j < 4; ++j) {
;                 if (j < 3) {
; #pragma unroll
;                     for (int dt = 0; dt < 4; ++dt) VLD(vf[(j + 1) & 1][dt], j + 1, dt);
;                 }
; #pragma unroll
;                 for (int dt = 0; dt < 4; ++dt) o[dt] = __builtin_amdgcn_mfma_f32_32x32x16_bf16(__builtin_bit_cast(bf16x8, vf[j & 1][dt]), pf[j], o[dt], 0, 0, 0);
;                 __builtin_amdgcn_sched_barrier(0); }
.LBB0_1082:
	v_sub_f32_e32 v66, v66, v203
	v_sub_f32_e32 v82, v82, v203
	v_exp_f32_e32 v66, v66
	v_exp_f32_e32 v82, v82
	v_sub_f32_e32 v67, v67, v203
	v_sub_f32_e32 v83, v83, v203
	v_exp_f32_e32 v67, v67
	v_exp_f32_e32 v83, v83
	v_sub_f32_e32 v68, v68, v203
	v_sub_f32_e32 v84, v84, v203
	v_exp_f32_e32 v68, v68
	v_exp_f32_e32 v84, v84
	v_sub_f32_e32 v69, v69, v203
	v_sub_f32_e32 v85, v85, v203
	v_exp_f32_e32 v69, v69
	v_exp_f32_e32 v85, v85
	v_sub_f32_e32 v70, v70, v203
	v_sub_f32_e32 v86, v86, v203
	v_add_f32_e32 v208, v82, v66
	v_exp_f32_e32 v70, v70
	v_exp_f32_e32 v86, v86
	v_sub_f32_e32 v71, v71, v203
	v_sub_f32_e32 v87, v87, v203
	v_add_f32_e32 v208, 0, v208
	v_add_f32_e32 v209, v83, v67
	v_exp_f32_e32 v71, v71
	v_exp_f32_e32 v87, v87
	v_sub_f32_e32 v72, v72, v203
	v_sub_f32_e32 v88, v88, v203
	v_add_f32_e32 v208, v209, v208
	v_add_f32_e32 v209, v84, v68
	v_exp_f32_e32 v72, v72
	v_exp_f32_e32 v88, v88
	v_sub_f32_e32 v73, v73, v203
	v_sub_f32_e32 v89, v89, v203
	v_add_f32_e32 v208, v209, v208
	v_add_f32_e32 v209, v85, v69
	v_exp_f32_e32 v73, v73
	v_exp_f32_e32 v89, v89
	v_sub_f32_e32 v74, v74, v203
	v_sub_f32_e32 v90, v90, v203
	v_add_f32_e32 v208, v209, v208
	v_add_f32_e32 v209, v86, v70
	v_exp_f32_e32 v74, v74
	v_exp_f32_e32 v90, v90
	v_sub_f32_e32 v75, v75, v203
	v_sub_f32_e32 v91, v91, v203
	v_add_f32_e32 v208, v209, v208
	v_add_f32_e32 v209, v87, v71
	v_exp_f32_e32 v75, v75
	v_exp_f32_e32 v91, v91
	v_sub_f32_e32 v76, v76, v203
	v_sub_f32_e32 v92, v92, v203
	v_add_f32_e32 v208, v209, v208
	v_add_f32_e32 v209, v88, v72
	v_exp_f32_e32 v76, v76
	v_exp_f32_e32 v92, v92
	v_sub_f32_e32 v77, v77, v203
	v_sub_f32_e32 v93, v93, v203
	v_add_f32_e32 v208, v209, v208
	v_add_f32_e32 v209, v89, v73
	v_exp_f32_e32 v77, v77
	v_exp_f32_e32 v93, v93
	v_sub_f32_e32 v78, v78, v203
	v_sub_f32_e32 v94, v94, v203
	v_add_f32_e32 v208, v209, v208
	v_add_f32_e32 v209, v90, v74
	v_exp_f32_e32 v78, v78
	v_exp_f32_e32 v94, v94
	v_sub_f32_e32 v79, v79, v203
	v_sub_f32_e32 v95, v95, v203
	v_add_f32_e32 v208, v209, v208
	v_add_f32_e32 v209, v91, v75
	v_exp_f32_e32 v79, v79
	v_exp_f32_e32 v95, v95
	v_sub_f32_e32 v80, v80, v203
	v_sub_f32_e32 v96, v96, v203
	v_add_f32_e32 v208, v209, v208
	v_add_f32_e32 v209, v92, v76
	v_exp_f32_e32 v80, v80
	v_exp_f32_e32 v96, v96
	v_sub_f32_e32 v81, v81, v203
	v_sub_f32_e32 v97, v97, v203
	v_add_f32_e32 v208, v209, v208
	v_add_f32_e32 v209, v93, v77
	v_exp_f32_e32 v81, v81
	v_exp_f32_e32 v97, v97
	v_add_f32_e32 v208, v209, v208
	v_add_f32_e32 v209, v94, v78
	v_add_f32_e32 v208, v209, v208
	v_add_f32_e32 v209, v95, v79
	v_add_f32_e32 v208, v209, v208
	v_cvt_pk_bf16_f32 v66, v66, v67
	v_cvt_pk_bf16_f32 v67, v68, v69
	v_cvt_pk_bf16_f32 v68, v70, v71
	v_cvt_pk_bf16_f32 v69, v72, v73
	v_add_f32_e32 v70, v96, v80
	v_add_f32_e32 v70, v70, v208
	v_mfma_f32_32x32x16_bf16 v[50:65], v[166:169], v[66:69], v[50:65]
	v_add_f32_e32 v71, v97, v81
	v_add_f32_e32 v166, v71, v70
	v_cvt_pk_bf16_f32 v70, v82, v83
	v_cvt_pk_bf16_f32 v71, v84, v85
	v_cvt_pk_bf16_f32 v72, v86, v87
	v_cvt_pk_bf16_f32 v73, v88, v89
	v_cvt_pk_bf16_f32 v74, v74, v75
	s_waitcnt lgkmcnt(2)
	v_mfma_f32_32x32x16_bf16 v[34:49], v[178:181], v[66:69], v[34:49]
	v_cvt_pk_bf16_f32 v75, v76, v77
	v_cvt_pk_bf16_f32 v76, v78, v79
	v_cvt_pk_bf16_f32 v77, v80, v81
	v_cvt_pk_bf16_f32 v78, v90, v91
	v_cvt_pk_bf16_f32 v79, v92, v93
	v_cvt_pk_bf16_f32 v80, v94, v95
	v_cvt_pk_bf16_f32 v81, v96, v97
	s_waitcnt lgkmcnt(1)
	v_mfma_f32_32x32x16_bf16 v[18:33], v[174:177], v[66:69], v[18:33]
	ds_read_b128 v[82:85], v204 offset:1056
	ds_read_b128 v[86:89], v205 offset:1568
	ds_read_b128 v[90:93], v206 offset:2080
	ds_read_b128 v[94:97], v207 offset:2592
	v_fmac_f32_e32 v166, v187, v196
	s_waitcnt lgkmcnt(4)
	v_mfma_f32_32x32x16_bf16 v[2:17], v[170:173], v[66:69], v[2:17]
	s_waitcnt lgkmcnt(3)
	v_mfma_f32_32x32x16_bf16 v[50:65], v[82:85], v[74:77], v[50:65]
	s_waitcnt lgkmcnt(2)
	v_mfma_f32_32x32x16_bf16 v[34:49], v[86:89], v[74:77], v[34:49]
	s_waitcnt lgkmcnt(1)
	v_mfma_f32_32x32x16_bf16 v[18:33], v[90:93], v[74:77], v[18:33]
	ds_read_b128 v[66:69], v204 offset:1088
	ds_read_b128 v[82:85], v205 offset:1600
	ds_read_b128 v[86:89], v206 offset:2112
	ds_read_b128 v[90:93], v207 offset:2624
	s_waitcnt lgkmcnt(4)
	v_mfma_f32_32x32x16_bf16 v[2:17], v[94:97], v[74:77], v[2:17]
	s_waitcnt lgkmcnt(3)
	v_mfma_f32_32x32x16_bf16 v[50:65], v[66:69], v[70:73], v[50:65]
	s_waitcnt lgkmcnt(2)
	v_mfma_f32_32x32x16_bf16 v[34:49], v[82:85], v[70:73], v[34:49]
	s_waitcnt lgkmcnt(1)
	v_mfma_f32_32x32x16_bf16 v[18:33], v[86:89], v[70:73], v[18:33]
	ds_read_b128 v[66:69], v204 offset:1120
	ds_read_b128 v[74:77], v205 offset:1632
	ds_read_b128 v[82:85], v206 offset:2144
	ds_read_b128 v[86:89], v207 offset:2656
	s_waitcnt lgkmcnt(4)
	v_mfma_f32_32x32x16_bf16 v[2:17], v[90:93], v[70:73], v[2:17]
	s_waitcnt lgkmcnt(3)
	v_mfma_f32_32x32x16_bf16 v[50:65], v[66:69], v[78:81], v[50:65]
	s_waitcnt lgkmcnt(2)
	v_mfma_f32_32x32x16_bf16 v[34:49], v[74:77], v[78:81], v[34:49]
	s_waitcnt lgkmcnt(1)
	v_mfma_f32_32x32x16_bf16 v[18:33], v[82:85], v[78:81], v[18:33]
	s_waitcnt lgkmcnt(0)
	v_mfma_f32_32x32x16_bf16 v[2:17], v[86:89], v[78:81], v[2:17]
	v_mov_b32_e32 v187, v166
	s_branch .LBB0_1084

; #define LAS __attribute__((address_space(3)))
; DI float shfl_xor_l(float v, int lane, int m) { return __int_as_float(__builtin_amdgcn_ds_bpermute((lane ^ m) << 2, __float_as_int(v))); }
; #define VLD(dst, j, dt) do { LAS unsigned char* va_ = vb + (32 * (dt) + n) * VROW + (16 * (j) + 4 * g) * 2; const u32x2 lo_ = *(const LAS u32x2*)(va_), hi_ = *(const LAS u32x2*)(va_ + 16); dst = (u32x4){lo_.x, lo_.y, hi_.x, hi_.y}; } while (0)
; DI void attn_unit(LAS unsigned char* lds, int wid, int b, int h, int qb) {
;     ...
;         if (kt <= cq) {
;             LAS unsigned char* kb = lds + buf * ABUF; LAS unsigned char* vb = kb + KBYTES;
;             f32x16 s0, s1;
; #pragma unroll
;             for (int i = 0; i < 16; ++i) { s0[i] = 0.f; s1[i] = 0.f; }
;     ...
;             bf16x8 ka[3][2];
;             ka[0][0] = KLD(0, 0); ka[0][1] = KLD(0, 1); ka[1][0] = KLD(1, 0); ka[1][1] = KLD(1, 1);
; #pragma unroll
;             for (int ks = 0; ks < 12; ++ks) {
;                 if (ks + 2 < 12) { ka[(ks + 2) % 3][0] = KLD(ks + 2, 0); ka[(ks + 2) % 3][1] = KLD(ks + 2, 1); }
;                 s0 = __builtin_amdgcn_mfma_f32_32x32x16_bf16(ka[ks % 3][0], qf[ks], s0, 0, 0, 0); s1 = __builtin_amdgcn_mfma_f32_32x32x16_bf16(ka[ks % 3][1], qf[ks], s1, 0, 0, 0);
;                 __builtin_amdgcn_sched_barrier(0); }
;             u32x4 vf[2][4];
; #pragma unroll
;             for (int dt = 0; dt < 4; ++dt) VLD(vf[0][dt], 0, dt);
;             float mx = s0[0];
; #pragma unroll
;             for (int i = 1; i < 16; ++i) mx = fmaxf(mx, s0[i]);
; #pragma unroll
;             for (int i = 0; i < 16; ++i) mx = fmaxf(mx, s1[i]);
;             mx = fmaxf(mx, shfl_xor_l(mx, lane, 32));
;             const float mnew = fmaxf(mrow, mx), alpha = __builtin_amdgcn_exp2f(mrow - mnew); mrow = mnew;
;     ...
;         if (kt + 1 < nkt) A_WRITE(buf ^ 1);
;         __syncthreads();
.LBB0_1084:
	s_xor_b32 s65, s65, 1
	s_mul_i32 s65, s65, 0xac00
	s_add_i32 s65, s65, 0
	v_add_u32_e32 v66, s65, v186
	s_waitcnt vmcnt(4)
	ds_write_b128 v66, v[146:149]
	s_waitcnt vmcnt(3)
	ds_write_b128 v66, v[150:153] offset:12800
	v_add_u32_e32 v66, s65, v188
	s_add_i32 s64, s64, 1
	s_waitcnt vmcnt(2)
	ds_write_b128 v66, v[154:157] offset:256
	v_add_u32_e32 v66, s65, v198
	v_add_u32_e32 v67, 0x6400, v66
	v_add_u32_e32 v66, 0x8800, v66
	v_lshl_add_u64 v[190:191], v[190:191], 0, s[10:11]
	v_lshl_add_u64 v[192:193], v[192:193], 0, s[12:13]
	s_cmp_eq_u32 s63, s64
	v_lshl_add_u64 v[194:195], v[194:195], 0, s[14:15]
	s_waitcnt vmcnt(1)
	ds_write2_b64 v67, v[158:159], v[160:161] offset1:2
	s_waitcnt vmcnt(0)
	ds_write2_b64 v66, v[162:163], v[164:165] offset1:2
	s_waitcnt lgkmcnt(0)
	s_barrier
	s_cbranch_scc1 .LBB0_1086
	v_mov_b32_e32 v170, v203
	s_branch .LBB0_1079
.LBB0_1086:
	s_or_b32 s61, s61, 2
	s_cmp_ge_u32 s61, s62
	s_cbranch_scc1 .LBB0_1090
	s_bitcmp1_b32 s63, 0
	s_cselect_b32 s61, 0xac00, 0
	s_add_i32 s61, s61, 0
	v_add3_u32 v162, s61, v199, v202
	ds_read_b128 v[66:69], v162
	ds_read_b128 v[146:149], v162 offset:32
	ds_read_b128 v[82:85], v162 offset:12800
	ds_read_b128 v[150:153], v162 offset:64
	ds_read_b128 v[154:157], v162 offset:12832
	ds_read_b128 v[158:161], v162 offset:12864
	s_waitcnt lgkmcnt(3)
	v_mfma_f32_32x32x16_bf16 v[82:97], v[82:85], v[142:145], 0
	v_mfma_f32_32x32x16_bf16 v[66:81], v[66:69], v[142:145], 0
	v_mfma_f32_32x32x16_bf16 v[66:81], v[146:149], v[138:141], v[66:81]
	ds_read_b128 v[142:145], v162 offset:96
	ds_read_b128 v[146:149], v162 offset:12896
	s_waitcnt lgkmcnt(3)
	v_mfma_f32_32x32x16_bf16 v[82:97], v[154:157], v[138:141], v[82:97]
	v_mfma_f32_32x32x16_bf16 v[66:81], v[150:153], v[134:137], v[66:81]
	ds_read_b128 v[138:141], v162 offset:128
	ds_read_b128 v[150:153], v162 offset:12928
	s_waitcnt lgkmcnt(4)
	v_mfma_f32_32x32x16_bf16 v[82:97], v[158:161], v[134:137], v[82:97]
	s_waitcnt lgkmcnt(3)
	v_mfma_f32_32x32x16_bf16 v[66:81], v[142:145], v[130:133], v[66:81]
	ds_read_b128 v[134:137], v162 offset:160
	ds_read_b128 v[142:145], v162 offset:12960
	s_waitcnt lgkmcnt(4)
	v_mfma_f32_32x32x16_bf16 v[82:97], v[146:149], v[130:133], v[82:97]
	s_waitcnt lgkmcnt(3)
	v_mfma_f32_32x32x16_bf16 v[66:81], v[138:141], v[126:129], v[66:81]
	ds_read_b128 v[130:133], v162 offset:192
	ds_read_b128 v[138:141], v162 offset:12992
	s_waitcnt lgkmcnt(4)
	v_mfma_f32_32x32x16_bf16 v[82:97], v[150:153], v[126:129], v[82:97]
	s_waitcnt lgkmcnt(3)
	v_mfma_f32_32x32x16_bf16 v[66:81], v[134:137], v[122:125], v[66:81]
	ds_read_b128 v[126:129], v162 offset:224
	ds_read_b128 v[134:137], v162 offset:13024
	s_waitcnt lgkmcnt(4)
	v_mfma_f32_32x32x16_bf16 v[82:97], v[142:145], v[122:125], v[82:97]
	s_waitcnt lgkmcnt(3)
	v_mfma_f32_32x32x16_bf16 v[66:81], v[130:133], v[118:121], v[66:81]
	ds_read_b128 v[122:125], v162 offset:256
	ds_read_b128 v[130:133], v162 offset:13056
	s_waitcnt lgkmcnt(4)
	v_mfma_f32_32x32x16_bf16 v[82:97], v[138:141], v[118:121], v[82:97]
	s_waitcnt lgkmcnt(3)
	v_mfma_f32_32x32x16_bf16 v[66:81], v[126:129], v[114:117], v[66:81]
	ds_read_b128 v[118:121], v162 offset:288
	ds_read_b128 v[126:129], v162 offset:13088
	s_waitcnt lgkmcnt(4)
	v_mfma_f32_32x32x16_bf16 v[82:97], v[134:137], v[114:117], v[82:97]
	s_waitcnt lgkmcnt(3)
	v_mfma_f32_32x32x16_bf16 v[66:81], v[122:125], v[110:113], v[66:81]
	ds_read_b128 v[114:117], v162 offset:320
	ds_read_b128 v[122:125], v162 offset:13120
	s_waitcnt lgkmcnt(4)
	v_mfma_f32_32x32x16_bf16 v[82:97], v[130:133], v[110:113], v[82:97]
	s_waitcnt lgkmcnt(3)
	v_mfma_f32_32x32x16_bf16 v[66:81], v[118:121], v[106:109], v[66:81]
	ds_read_b128 v[110:113], v162 offset:352
	ds_read_b128 v[118:121], v162 offset:13152
	s_waitcnt lgkmcnt(4)
	v_mfma_f32_32x32x16_bf16 v[82:97], v[126:129], v[106:109], v[82:97]
	s_waitcnt lgkmcnt(3)
	v_mfma_f32_32x32x16_bf16 v[66:81], v[114:117], v[102:105], v[66:81]
	s_waitcnt lgkmcnt(2)
	v_mfma_f32_32x32x16_bf16 v[82:97], v[122:125], v[102:105], v[82:97]
	s_waitcnt lgkmcnt(1)
	v_mfma_f32_32x32x16_bf16 v[66:81], v[110:113], v[98:101], v[66:81]
	v_add_u32_e32 v102, s61, v184
	v_add_u32_e32 v122, v102, v189
	v_add_u32_e32 v122, v122, v184
	v_add_u32_e32 v115, 0x6000, v122
	v_add_u32_e32 v116, 0x7000, v122
	v_add_u32_e32 v117, 0x8000, v122
	ds_read_b128 v[102:105], v115 offset:1024
	ds_read_b128 v[110:113], v116 offset:1536
	s_nop 4
	v_max_f32_e32 v106, v67, v67
	v_max_f32_e32 v107, v66, v66
	v_max_f32_e32 v106, v107, v106
	s_waitcnt lgkmcnt(2)
	v_mfma_f32_32x32x16_bf16 v[82:97], v[118:121], v[98:101], v[82:97]
	v_max3_f32 v106, v106, v68, v69
	v_max3_f32 v106, v106, v70, v71
	v_max3_f32 v106, v106, v72, v73
	v_max3_f32 v106, v106, v74, v75
	v_max3_f32 v106, v106, v76, v77
	v_max3_f32 v106, v106, v78, v79
	v_max3_f32 v106, v106, v80, v81
	s_nop 4
	v_max3_f32 v98, v106, v82, v83
	v_max3_f32 v98, v98, v84, v85
	v_max3_f32 v98, v98, v86, v87
	v_max3_f32 v98, v98, v88, v89
	v_max3_f32 v98, v98, v90, v91
	v_max3_f32 v98, v98, v92, v93
	v_max3_f32 v98, v98, v94, v95
	v_max3_f32 v98, v98, v96, v97
	ds_bpermute_b32 v99, v185, v98
	v_add_u32_e32 v118, 0x9000, v122
	ds_read_b128 v[106:109], v117 offset:2048
	s_waitcnt lgkmcnt(1)
	v_max3_f32 v119, v203, v98, v99
	v_sub_f32_e32 v98, v203, v119
	v_exp_f32_e32 v114, v98
	ds_read_b128 v[98:101], v118 offset:2560
	v_cmp_neq_f32_e32 vcc, 1.0, v114
	s_cbranch_vccz .LBB0_1089
; DI unsigned pk2(float a, float b) { f32x2 f = {a, b}; bf16v2 r = __builtin_convertvector(f, bf16v2); return __builtin_bit_cast(unsigned, r); }
; #define VLD(dst, j, dt) do { LAS unsigned char* va_ = vb + (32 * (dt) + n) * VROW + (16 * (j) + 4 * g) * 2; const u32x2 lo_ = *(const LAS u32x2*)(va_), hi_ = *(const LAS u32x2*)(va_ + 16); dst = (u32x4){lo_.x, lo_.y, hi_.x, hi_.y}; } while (0)
; DI void attn_unit(LAS unsigned char* lds, int wid, int b, int h, int qb) {
;     ...
;             float ls = 0.f;
; #pragma unroll
;             for (int i = 0; i < 16; ++i) { s0[i] = __builtin_amdgcn_exp2f(s0[i] - mnew); s1[i] = __builtin_amdgcn_exp2f(s1[i] - mnew); ls += s0[i] + s1[i]; }
;             lrow = lrow * alpha + ls;
;             if (__builtin_amdgcn_ballot_w64(alpha != 1.f) != 0ull) {
; #pragma unroll
;                 for (int dt = 0; dt < 4; ++dt)
; #pragma unroll
;                     for (int i = 0; i < 16; ++i) o[dt][i] *= alpha;
;             }
;             bf16x8 pf[4];
; #pragma unroll
;             for (int jj = 0; jj < 2; ++jj) { u32x4 w0, w1;
;                 w0.x = pk2(s0[8 * jj + 0], s0[8 * jj + 1]); w0.y = pk2(s0[8 * jj + 2], s0[8 * jj + 3]); w0.z = pk2(s0[8 * jj + 4], s0[8 * jj + 5]); w0.w = pk2(s0[8 * jj + 6], s0[8 * jj + 7]);
;                 w1.x = pk2(s1[8 * jj + 0], s1[8 * jj + 1]); w1.y = pk2(s1[8 * jj + 2], s1[8 * jj + 3]); w1.z = pk2(s1[8 * jj + 4], s1[8 * jj + 5]); w1.w = pk2(s1[8 * jj + 6], s1[8 * jj + 7]);
;                 pf[jj] = __builtin_bit_cast(bf16x8, w0); pf[2 + jj] = __builtin_bit_cast(bf16x8, w1); }
; #pragma unroll
;             for (int j = 0; j < 4; ++j) {
;                 if (j < 3) {
; #pragma unroll
;                     for (int dt = 0; dt < 4; ++dt) VLD(vf[(j + 1) & 1][dt], j + 1, dt);
;                 }
; #pragma unroll
;                 for (int dt = 0; dt < 4; ++dt) o[dt] = __builtin_amdgcn_mfma_f32_32x32x16_bf16(__builtin_bit_cast(bf16x8, vf[j & 1][dt]), pf[j], o[dt], 0, 0, 0);
;                 __builtin_amdgcn_sched_barrier(0); }
	v_pk_mul_f32 v[64:65], v[64:65], v[114:115] op_sel_hi:[1,0]
	v_pk_mul_f32 v[62:63], v[62:63], v[114:115] op_sel_hi:[1,0]
	v_pk_mul_f32 v[60:61], v[60:61], v[114:115] op_sel_hi:[1,0]
	v_pk_mul_f32 v[58:59], v[58:59], v[114:115] op_sel_hi:[1,0]
	v_pk_mul_f32 v[56:57], v[56:57], v[114:115] op_sel_hi:[1,0]
	v_pk_mul_f32 v[54:55], v[54:55], v[114:115] op_sel_hi:[1,0]
	v_pk_mul_f32 v[52:53], v[52:53], v[114:115] op_sel_hi:[1,0]
	v_pk_mul_f32 v[50:51], v[50:51], v[114:115] op_sel_hi:[1,0]
	v_pk_mul_f32 v[48:49], v[48:49], v[114:115] op_sel_hi:[1,0]
	v_pk_mul_f32 v[46:47], v[46:47], v[114:115] op_sel_hi:[1,0]
	v_pk_mul_f32 v[44:45], v[44:45], v[114:115] op_sel_hi:[1,0]
	v_pk_mul_f32 v[42:43], v[42:43], v[114:115] op_sel_hi:[1,0]
	v_pk_mul_f32 v[40:41], v[40:41], v[114:115] op_sel_hi:[1,0]
	v_pk_mul_f32 v[38:39], v[38:39], v[114:115] op_sel_hi:[1,0]
	v_pk_mul_f32 v[36:37], v[36:37], v[114:115] op_sel_hi:[1,0]
	v_pk_mul_f32 v[34:35], v[34:35], v[114:115] op_sel_hi:[1,0]
	v_pk_mul_f32 v[32:33], v[32:33], v[114:115] op_sel_hi:[1,0]
	v_pk_mul_f32 v[30:31], v[30:31], v[114:115] op_sel_hi:[1,0]
	v_pk_mul_f32 v[28:29], v[28:29], v[114:115] op_sel_hi:[1,0]
	v_pk_mul_f32 v[26:27], v[26:27], v[114:115] op_sel_hi:[1,0]
	v_pk_mul_f32 v[24:25], v[24:25], v[114:115] op_sel_hi:[1,0]
	v_pk_mul_f32 v[22:23], v[22:23], v[114:115] op_sel_hi:[1,0]
	v_pk_mul_f32 v[20:21], v[20:21], v[114:115] op_sel_hi:[1,0]
	v_pk_mul_f32 v[18:19], v[18:19], v[114:115] op_sel_hi:[1,0]
	v_pk_mul_f32 v[16:17], v[16:17], v[114:115] op_sel_hi:[1,0]
	v_pk_mul_f32 v[14:15], v[14:15], v[114:115] op_sel_hi:[1,0]
	v_pk_mul_f32 v[12:13], v[12:13], v[114:115] op_sel_hi:[1,0]
	v_pk_mul_f32 v[10:11], v[10:11], v[114:115] op_sel_hi:[1,0]
	v_pk_mul_f32 v[8:9], v[8:9], v[114:115] op_sel_hi:[1,0]
	v_pk_mul_f32 v[6:7], v[6:7], v[114:115] op_sel_hi:[1,0]
	v_pk_mul_f32 v[4:5], v[4:5], v[114:115] op_sel_hi:[1,0]
	v_pk_mul_f32 v[2:3], v[2:3], v[114:115] op_sel_hi:[1,0]
.LBB0_1089:
	v_sub_f32_e32 v66, v66, v119
	v_sub_f32_e32 v82, v82, v119
	v_exp_f32_e32 v66, v66
	v_exp_f32_e32 v82, v82
	v_sub_f32_e32 v67, v67, v119
	v_sub_f32_e32 v83, v83, v119
	v_exp_f32_e32 v67, v67
	v_exp_f32_e32 v83, v83
	v_sub_f32_e32 v68, v68, v119
	v_sub_f32_e32 v84, v84, v119
	v_exp_f32_e32 v68, v68
	v_exp_f32_e32 v84, v84
	v_sub_f32_e32 v69, v69, v119
	v_sub_f32_e32 v85, v85, v119
	v_exp_f32_e32 v69, v69
	v_exp_f32_e32 v85, v85
	v_sub_f32_e32 v70, v70, v119
	v_sub_f32_e32 v86, v86, v119
	v_add_f32_e32 v120, v82, v66
	v_exp_f32_e32 v70, v70
	v_exp_f32_e32 v86, v86
	v_sub_f32_e32 v71, v71, v119
	v_sub_f32_e32 v87, v87, v119
	v_add_f32_e32 v120, 0, v120
	v_add_f32_e32 v121, v83, v67
	v_exp_f32_e32 v71, v71
	v_exp_f32_e32 v87, v87
	v_sub_f32_e32 v72, v72, v119
	v_sub_f32_e32 v88, v88, v119
	v_add_f32_e32 v120, v121, v120
	v_add_f32_e32 v121, v84, v68
	v_exp_f32_e32 v72, v72
	v_exp_f32_e32 v88, v88
	v_sub_f32_e32 v73, v73, v119
	v_sub_f32_e32 v89, v89, v119
	v_add_f32_e32 v120, v121, v120
	v_add_f32_e32 v121, v85, v69
	v_exp_f32_e32 v73, v73
	v_exp_f32_e32 v89, v89
	v_sub_f32_e32 v74, v74, v119
	v_sub_f32_e32 v90, v90, v119
	v_add_f32_e32 v120, v121, v120
	v_add_f32_e32 v121, v86, v70
	v_exp_f32_e32 v74, v74
	v_exp_f32_e32 v90, v90
	v_sub_f32_e32 v75, v75, v119
	v_sub_f32_e32 v91, v91, v119
	v_add_f32_e32 v120, v121, v120
	v_add_f32_e32 v121, v87, v71
	v_exp_f32_e32 v75, v75
	v_exp_f32_e32 v91, v91
	v_sub_f32_e32 v76, v76, v119
	v_sub_f32_e32 v92, v92, v119
	v_add_f32_e32 v120, v121, v120
	v_add_f32_e32 v121, v88, v72
	v_exp_f32_e32 v76, v76
	v_exp_f32_e32 v92, v92
	v_sub_f32_e32 v77, v77, v119
	v_sub_f32_e32 v93, v93, v119
	v_add_f32_e32 v120, v121, v120
	v_add_f32_e32 v121, v89, v73
	v_exp_f32_e32 v77, v77
	v_exp_f32_e32 v93, v93
	v_sub_f32_e32 v78, v78, v119
	v_sub_f32_e32 v94, v94, v119
	v_add_f32_e32 v120, v121, v120
	v_add_f32_e32 v121, v90, v74
	v_exp_f32_e32 v78, v78
	v_exp_f32_e32 v94, v94
	v_sub_f32_e32 v79, v79, v119
	v_sub_f32_e32 v95, v95, v119
	v_add_f32_e32 v120, v121, v120
	v_add_f32_e32 v121, v91, v75
	v_exp_f32_e32 v79, v79
	v_exp_f32_e32 v95, v95
	v_sub_f32_e32 v80, v80, v119
	v_sub_f32_e32 v96, v96, v119
	v_add_f32_e32 v120, v121, v120
	v_add_f32_e32 v121, v92, v76
	v_exp_f32_e32 v80, v80
	v_exp_f32_e32 v96, v96
	v_sub_f32_e32 v81, v81, v119
	v_sub_f32_e32 v97, v97, v119
	v_add_f32_e32 v120, v121, v120
	v_add_f32_e32 v121, v93, v77
	v_exp_f32_e32 v81, v81
	v_exp_f32_e32 v97, v97
	v_add_f32_e32 v120, v121, v120
	v_add_f32_e32 v121, v94, v78
	v_add_f32_e32 v120, v121, v120
	v_add_f32_e32 v121, v95, v79
	v_add_f32_e32 v120, v121, v120
	v_cvt_pk_bf16_f32 v66, v66, v67
	v_cvt_pk_bf16_f32 v67, v68, v69
	v_cvt_pk_bf16_f32 v68, v70, v71
	v_cvt_pk_bf16_f32 v69, v72, v73
	v_add_f32_e32 v70, v96, v80
	v_add_f32_e32 v70, v70, v120
	v_mfma_f32_32x32x16_bf16 v[50:65], v[102:105], v[66:69], v[50:65]
	v_add_f32_e32 v71, v97, v81
	v_add_f32_e32 v102, v71, v70
	v_cvt_pk_bf16_f32 v70, v82, v83
	v_cvt_pk_bf16_f32 v71, v84, v85
	v_cvt_pk_bf16_f32 v72, v86, v87
	v_cvt_pk_bf16_f32 v73, v88, v89
	v_cvt_pk_bf16_f32 v74, v74, v75
	v_mfma_f32_32x32x16_bf16 v[34:49], v[110:113], v[66:69], v[34:49]
	v_cvt_pk_bf16_f32 v75, v76, v77
	v_cvt_pk_bf16_f32 v76, v78, v79
	v_cvt_pk_bf16_f32 v77, v80, v81
	v_cvt_pk_bf16_f32 v78, v90, v91
	v_cvt_pk_bf16_f32 v79, v92, v93
	v_cvt_pk_bf16_f32 v80, v94, v95
	v_cvt_pk_bf16_f32 v81, v96, v97
	s_waitcnt lgkmcnt(1)
	v_mfma_f32_32x32x16_bf16 v[18:33], v[106:109], v[66:69], v[18:33]
	ds_read_b128 v[82:85], v115 offset:1056
	ds_read_b128 v[86:89], v116 offset:1568
	ds_read_b128 v[90:93], v117 offset:2080
	ds_read_b128 v[94:97], v118 offset:2592
	v_fmac_f32_e32 v102, v187, v114
	s_waitcnt lgkmcnt(4)
; #define LAS __attribute__((address_space(3)))
; DI u32x2 pk4(f32x4 v) { u32x2 r; r.x = pk2(v[0], v[1]); r.y = pk2(v[2], v[3]); return r; }
; DI float shfl_xor_l(float v, int lane, int m) { return __int_as_float(__builtin_amdgcn_ds_bpermute((lane ^ m) << 2, __float_as_int(v))); }
; #define VLD(dst, j, dt) do { LAS unsigned char* va_ = vb + (32 * (dt) + n) * VROW + (16 * (j) + 4 * g) * 2; const u32x2 lo_ = *(const LAS u32x2*)(va_), hi_ = *(const LAS u32x2*)(va_ + 16); dst = (u32x4){lo_.x, lo_.y, hi_.x, hi_.y}; } while (0)
; DI void attn_unit(LAS unsigned char* lds, int wid, int b, int h, int qb) {
;     ...
;             for (int j = 0; j < 4; ++j) {
;                 if (j < 3) {
; #pragma unroll
;                     for (int dt = 0; dt < 4; ++dt) VLD(vf[(j + 1) & 1][dt], j + 1, dt);
;                 }
; #pragma unroll
;                 for (int dt = 0; dt < 4; ++dt) o[dt] = __builtin_amdgcn_mfma_f32_32x32x16_bf16(__builtin_bit_cast(bf16x8, vf[j & 1][dt]), pf[j], o[dt], 0, 0, 0);
;                 __builtin_amdgcn_sched_barrier(0); }
;     ...
;         }
;         if (kt + 1 < nkt) A_WRITE(buf ^ 1);
;         __syncthreads();
;     }
;     ...
;     const float lt = lrow + shfl_xor_l(lrow, lane, 32), inv = 1.f / lt;
;     LAS unsigned char* pt_ = lds + ABUF + wid * (32 * 272);
; #pragma unroll
;     for (int dt = 0; dt < 4; ++dt)
; #pragma unroll
;         for (int blk = 0; blk < 4; ++blk) { const f32x4 v = {o[dt][4 * blk] * inv, o[dt][4 * blk + 1] * inv, o[dt][4 * blk + 2] * inv, o[dt][4 * blk + 3] * inv};
;             *(LAS u32x2*)(pt_ + n * 272 + (32 * dt + 8 * blk + 4 * g) * 2) = pk4(v); }
;     asm volatile("" ::: "memory");
;     bf16_t* od = WSB(OFF_O) + ((size_t)b * SEQ + q0 + (lane >> 4)) * 2048 + h * 128 + (lane & 15) * 8;
; #pragma unroll
;     for (int j = 0; j < 8; ++j) { const u32x4 w = *(const LAS u32x4*)(pt_ + (4 * j + (lane >> 4)) * 272 + (lane & 15) * 16); *(u32x4*)(od + (size_t)(4 * j) * 2048) = w; }
;     asm volatile("" ::: "memory");
	v_mfma_f32_32x32x16_bf16 v[2:17], v[98:101], v[66:69], v[2:17]
	s_waitcnt lgkmcnt(3)
	v_mfma_f32_32x32x16_bf16 v[50:65], v[82:85], v[74:77], v[50:65]
	s_waitcnt lgkmcnt(2)
	v_mfma_f32_32x32x16_bf16 v[34:49], v[86:89], v[74:77], v[34:49]
	s_waitcnt lgkmcnt(1)
	v_mfma_f32_32x32x16_bf16 v[18:33], v[90:93], v[74:77], v[18:33]
	ds_read_b128 v[66:69], v115 offset:1088
	ds_read_b128 v[82:85], v116 offset:1600
	ds_read_b128 v[86:89], v117 offset:2112
	ds_read_b128 v[90:93], v118 offset:2624
	s_waitcnt lgkmcnt(4)
	v_mfma_f32_32x32x16_bf16 v[2:17], v[94:97], v[74:77], v[2:17]
	s_waitcnt lgkmcnt(3)
	v_mfma_f32_32x32x16_bf16 v[50:65], v[66:69], v[70:73], v[50:65]
	s_waitcnt lgkmcnt(2)
	v_mfma_f32_32x32x16_bf16 v[34:49], v[82:85], v[70:73], v[34:49]
	s_waitcnt lgkmcnt(1)
	v_mfma_f32_32x32x16_bf16 v[18:33], v[86:89], v[70:73], v[18:33]
	ds_read_b128 v[66:69], v115 offset:1120
	ds_read_b128 v[74:77], v116 offset:1632
	ds_read_b128 v[82:85], v117 offset:2144
	ds_read_b128 v[86:89], v118 offset:2656
	s_waitcnt lgkmcnt(4)
	v_mfma_f32_32x32x16_bf16 v[2:17], v[90:93], v[70:73], v[2:17]
	s_waitcnt lgkmcnt(3)
	v_mfma_f32_32x32x16_bf16 v[50:65], v[66:69], v[78:81], v[50:65]
	s_waitcnt lgkmcnt(2)
	v_mfma_f32_32x32x16_bf16 v[34:49], v[74:77], v[78:81], v[34:49]
	s_waitcnt lgkmcnt(1)
	v_mfma_f32_32x32x16_bf16 v[18:33], v[82:85], v[78:81], v[18:33]
	s_waitcnt lgkmcnt(0)
	v_mfma_f32_32x32x16_bf16 v[2:17], v[86:89], v[78:81], v[2:17]
	v_mov_b32_e32 v187, v102
.LBB0_1090:
	ds_bpermute_b32 v66, v185, v187
	s_waitcnt lgkmcnt(0)
	s_barrier
	v_mov_b32_e32 v185, v1
	v_add_f32_e32 v66, v187, v66
	v_div_scale_f32 v67, s[62:63], v66, v66, 1.0
	v_rcp_f32_e32 v68, v67
	v_div_scale_f32 v69, vcc, 1.0, v66, 1.0
	v_mov_b32_e32 v187, v201
	v_fma_f32 v70, -v67, v68, 1.0
	v_fmac_f32_e32 v68, v70, v68
	v_mul_f32_e32 v70, v69, v68
	v_fma_f32 v71, -v67, v70, v69
	v_fmac_f32_e32 v70, v71, v68
	v_fma_f32 v67, -v67, v70, v69
	v_div_fmas_f32 v67, v67, v68, v70
	v_div_fixup_f32 v66, v67, v66, 1.0
	v_mul_u32_u24_e32 v67, 0x110, v197
	v_add3_u32 v67, s30, v67, v184
	v_pk_mul_f32 v[2:3], v[2:3], v[66:67] op_sel_hi:[1,0]
	v_pk_mul_f32 v[4:5], v[4:5], v[66:67] op_sel_hi:[1,0]
	v_pk_mul_f32 v[50:51], v[50:51], v[66:67] op_sel_hi:[1,0]
	v_pk_mul_f32 v[52:53], v[52:53], v[66:67] op_sel_hi:[1,0]
	v_cvt_pk_bf16_f32 v2, v2, v3
	v_cvt_pk_bf16_f32 v3, v4, v5
	v_pk_mul_f32 v[4:5], v[6:7], v[66:67] op_sel_hi:[1,0]
	v_pk_mul_f32 v[6:7], v[8:9], v[66:67] op_sel_hi:[1,0]
	v_cvt_pk_bf16_f32 v50, v50, v51
	v_cvt_pk_bf16_f32 v51, v52, v53
	v_pk_mul_f32 v[52:53], v[54:55], v[66:67] op_sel_hi:[1,0]
	v_pk_mul_f32 v[54:55], v[56:57], v[66:67] op_sel_hi:[1,0]
	v_add_u32_e32 v56, 0xac00, v67
	v_cvt_pk_bf16_f32 v4, v4, v5
	v_cvt_pk_bf16_f32 v5, v6, v7
	ds_write2_b64 v56, v[2:3], v[4:5] offset0:24 offset1:26
	v_pk_mul_f32 v[2:3], v[10:11], v[66:67] op_sel_hi:[1,0]
	v_pk_mul_f32 v[4:5], v[12:13], v[66:67] op_sel_hi:[1,0]
	v_pk_mul_f32 v[34:35], v[34:35], v[66:67] op_sel_hi:[1,0]
	v_pk_mul_f32 v[36:37], v[36:37], v[66:67] op_sel_hi:[1,0]
	v_pk_mul_f32 v[18:19], v[18:19], v[66:67] op_sel_hi:[1,0]
	v_pk_mul_f32 v[20:21], v[20:21], v[66:67] op_sel_hi:[1,0]
	v_cvt_pk_bf16_f32 v2, v2, v3
	v_cvt_pk_bf16_f32 v3, v4, v5
	v_pk_mul_f32 v[4:5], v[14:15], v[66:67] op_sel_hi:[1,0]
	v_pk_mul_f32 v[6:7], v[16:17], v[66:67] op_sel_hi:[1,0]
	v_cvt_pk_bf16_f32 v34, v34, v35
	v_cvt_pk_bf16_f32 v35, v36, v37
	v_pk_mul_f32 v[36:37], v[38:39], v[66:67] op_sel_hi:[1,0]
	v_pk_mul_f32 v[38:39], v[40:41], v[66:67] op_sel_hi:[1,0]
	v_cvt_pk_bf16_f32 v18, v18, v19
	v_cvt_pk_bf16_f32 v19, v20, v21
	v_pk_mul_f32 v[20:21], v[22:23], v[66:67] op_sel_hi:[1,0]
	v_pk_mul_f32 v[22:23], v[24:25], v[66:67] op_sel_hi:[1,0]
	v_cvt_pk_bf16_f32 v4, v4, v5
	v_cvt_pk_bf16_f32 v5, v6, v7
	v_cvt_pk_bf16_f32 v52, v52, v53
	v_cvt_pk_bf16_f32 v53, v54, v55
	v_cvt_pk_bf16_f32 v36, v36, v37
	v_cvt_pk_bf16_f32 v37, v38, v39
	v_cvt_pk_bf16_f32 v20, v20, v21
	v_cvt_pk_bf16_f32 v21, v22, v23
	ds_write2_b64 v56, v[2:3], v[4:5] offset0:28 offset1:30
	v_ashrrev_i32_e32 v2, 4, v183
	ds_write2_b64 v56, v[50:51], v[52:53] offset1:2
	v_pk_mul_f32 v[50:51], v[58:59], v[66:67] op_sel_hi:[1,0]
	v_pk_mul_f32 v[52:53], v[60:61], v[66:67] op_sel_hi:[1,0]
	ds_write2_b64 v56, v[34:35], v[36:37] offset0:8 offset1:10
	v_pk_mul_f32 v[34:35], v[42:43], v[66:67] op_sel_hi:[1,0]
	v_pk_mul_f32 v[36:37], v[44:45], v[66:67] op_sel_hi:[1,0]
	ds_write2_b64 v56, v[18:19], v[20:21] offset0:16 offset1:18
	v_pk_mul_f32 v[18:19], v[26:27], v[66:67] op_sel_hi:[1,0]
	v_pk_mul_f32 v[20:21], v[28:29], v[66:67] op_sel_hi:[1,0]
	v_ashrrev_i32_e32 v3, 31, v2
	v_cvt_pk_bf16_f32 v50, v50, v51
	v_cvt_pk_bf16_f32 v51, v52, v53
	v_pk_mul_f32 v[52:53], v[62:63], v[66:67] op_sel_hi:[1,0]
	v_pk_mul_f32 v[54:55], v[64:65], v[66:67] op_sel_hi:[1,0]
	v_cvt_pk_bf16_f32 v34, v34, v35
	v_cvt_pk_bf16_f32 v35, v36, v37
	v_pk_mul_f32 v[36:37], v[46:47], v[66:67] op_sel_hi:[1,0]
	v_pk_mul_f32 v[38:39], v[48:49], v[66:67] op_sel_hi:[1,0]
	v_cvt_pk_bf16_f32 v18, v18, v19
	v_cvt_pk_bf16_f32 v19, v20, v21
	v_pk_mul_f32 v[20:21], v[30:31], v[66:67] op_sel_hi:[1,0]
	v_pk_mul_f32 v[22:23], v[32:33], v[66:67] op_sel_hi:[1,0]
	v_lshl_add_u64 v[4:5], s[26:27], 0, v[2:3]
	v_cvt_pk_bf16_f32 v52, v52, v53
	v_cvt_pk_bf16_f32 v53, v54, v55
	v_cvt_pk_bf16_f32 v36, v36, v37
	v_cvt_pk_bf16_f32 v37, v38, v39
	v_cvt_pk_bf16_f32 v20, v20, v21
	v_cvt_pk_bf16_f32 v21, v22, v23
	v_lshlrev_b64 v[4:5], 12, v[4:5]
	ds_write2_b64 v56, v[50:51], v[52:53] offset0:4 offset1:6
	ds_write2_b64 v56, v[34:35], v[36:37] offset0:12 offset1:14
	ds_write2_b64 v56, v[18:19], v[20:21] offset0:20 offset1:22
	v_lshl_add_u64 v[4:5], s[24:25], 0, v[4:5]
	s_lshl_b32 s24, s4, 1
	s_mov_b32 s25, s5
	v_mul_lo_u32 v2, v2, s46
	v_lshl_add_u64 v[4:5], v[4:5], 0, s[24:25]
	v_lshlrev_b32_e32 v6, 1, v182
	v_mov_b32_e32 v7, v1
	v_add3_u32 v0, s30, v0, v2
	v_lshl_add_u64 v[10:11], v[4:5], 0, v[6:7]
	ds_read_b128 v[2:5], v0 offset:44032
	ds_read_b128 v[6:9], v0 offset:45120
	v_add_co_u32_e32 v12, vcc, s47, v10
	s_mov_b64 s[26:27], s[0:1]
	s_nop 0
	v_addc_co_u32_e32 v13, vcc, 0, v11, vcc
	s_waitcnt lgkmcnt(1)
; #define LAS __attribute__((address_space(3)))
; DI int lane_id() { int l = __builtin_amdgcn_mbcnt_hi(-1, __builtin_amdgcn_mbcnt_lo(-1, 0)); asm volatile("" : "+v"(l)); return l; }
; #define A_LOAD(kt) do { const size_t ko = (size_t)(kt) * 64; st0 = *(const u32x4*)(kn_src + ko * 2048); st1 = *(const u32x4*)(kn_src + (ko + 32) * 2048); \
;         st2 = *(const u32x4*)(kr_src + ko * 64); st3 = *(const u32x4*)(v_src + ko); st4 = *(const u32x4*)(v_src + ko + (size_t)64 * 8192); } while (0)
; DI void attn_unit(LAS unsigned char* lds, int wid, int b, int h, int qb) {
;     ...
;     const int lane = lane_id(), tid = wid * 64 + lane, n = lane & 31, g = lane >> 5;
;     const int q0 = qb * 256 + wid * 32, cq = q0 >> 6, nkt = 4 * qb + 4;
;     const size_t tokq = (size_t)b * SEQ + q0 + n;
;     const bf16_t* Q = WSB(OFF_Q); const bf16_t* KN = WSB(OFF_KN); const bf16_t* KR = WSB(OFF_KR); const bf16_t* VT = WSB(OFF_VT2);
;     bf16x8 qf[12];
; #pragma unroll
;     for (int ks = 0; ks < 12; ++ks) qf[ks] = *(const bf16x8*)(Q + tokq * 3072 + h * 192 + ks * 16 + g * 8);
;     f32x16 o[4];
; #pragma unroll
;     for (int dt = 0; dt < 4; ++dt)
; #pragma unroll
;         for (int i = 0; i < 16; ++i) o[dt][i] = 0.f;
;     float mrow = -__builtin_inff(), lrow = 0.f;
;     const int krow = tid >> 4, kc16 = tid & 15, rrow = tid >> 3, rc8 = tid & 7;
;     const bf16_t* kn_src = KN + ((size_t)b * SEQ + krow) * 2048 + h * 128 + kc16 * 8;
;     const bf16_t* kr_src = KR + ((size_t)b * SEQ + rrow) * 64 + rc8 * 8;
;     const bf16_t* v_src = VT + ((size_t)h * 128 + rrow) * 8192 + (size_t)b * SEQ + rc8 * 8;
;     const int kn_dst = krow * KROW + kc16 * 16, kr_dst = rrow * KROW + 256 + rc8 * 16, v_dst = KBYTES + rrow * VROW + rc8 * 16;
;     u32x4 st0, st1, st2, st3, st4;
;     ...
;     A_LOAD(0); A_WRITE(0); __syncthreads();
;     ...
;     bf16_t* od = WSB(OFF_O) + ((size_t)b * SEQ + q0 + (lane >> 4)) * 2048 + h * 128 + (lane & 15) * 8;
; #pragma unroll
;     for (int j = 0; j < 8; ++j) { const u32x4 w = *(const LAS u32x4*)(pt_ + (4 * j + (lane >> 4)) * 272 + (lane & 15) * 16); *(u32x4*)(od + (size_t)(4 * j) * 2048) = w; }
	global_store_dwordx4 v[12:13], v[2:5], off
	v_mov_b32_e32 v172, 0xff800000
	s_nop 0
	v_add_co_u32_e32 v2, vcc, s48, v10
	s_nop 1
	v_addc_co_u32_e32 v3, vcc, 0, v11, vcc
	s_waitcnt lgkmcnt(0)
	global_store_dwordx4 v[2:3], v[6:9], off
	ds_read_b128 v[2:5], v0 offset:46208
	ds_read_b128 v[6:9], v0 offset:47296
	v_add_co_u32_e32 v12, vcc, s49, v10
	s_nop 1
	v_addc_co_u32_e32 v13, vcc, 0, v11, vcc
	s_waitcnt lgkmcnt(1)
	global_store_dwordx4 v[12:13], v[2:5], off
	s_nop 1
	v_add_co_u32_e32 v2, vcc, s50, v10
	s_nop 1
	v_addc_co_u32_e32 v3, vcc, 0, v11, vcc
	s_waitcnt lgkmcnt(0)
	global_store_dwordx4 v[2:3], v[6:9], off
	ds_read_b128 v[2:5], v0 offset:48384
	ds_read_b128 v[6:9], v0 offset:49472
	v_add_co_u32_e32 v12, vcc, s51, v10
	s_nop 1
	v_addc_co_u32_e32 v13, vcc, 0, v11, vcc
	s_waitcnt lgkmcnt(1)
	global_store_dwordx4 v[12:13], v[2:5], off
	s_nop 1
	v_add_co_u32_e32 v2, vcc, s52, v10
	s_nop 1
	v_addc_co_u32_e32 v3, vcc, 0, v11, vcc
	s_waitcnt lgkmcnt(0)
	global_store_dwordx4 v[2:3], v[6:9], off
	ds_read_b128 v[2:5], v0 offset:50560
	ds_read_b128 v[6:9], v0 offset:51648
	v_add_co_u32_e32 v12, vcc, s53, v10
	s_nop 1
	v_addc_co_u32_e32 v13, vcc, 0, v11, vcc
	s_waitcnt lgkmcnt(1)
	global_store_dwordx4 v[12:13], v[2:5], off
	s_nop 1
	v_add_co_u32_e32 v2, vcc, s54, v10
	s_nop 1
	v_addc_co_u32_e32 v3, vcc, 0, v11, vcc
	s_waitcnt lgkmcnt(0)
	global_store_dwordx4 v[2:3], v[6:9], off
	s_load_dwordx2 s[26:27], s[26:27], 0xa8
	v_add_u32_e32 v0, s28, v187
	v_ashrrev_i32_e32 v24, 3, v0
	v_ashrrev_i32_e32 v25, 31, v24
	v_ashrrev_i32_e32 v22, 4, v0
	v_lshl_add_u64 v[4:5], s[16:17], 0, v[24:25]
	v_ashrrev_i32_e32 v23, 31, v22
	v_lshlrev_b64 v[4:5], 7, v[4:5]
	v_lshlrev_b32_e32 v0, 4, v187
	v_lshl_add_u64 v[2:3], s[16:17], 0, v[22:23]
	s_waitcnt lgkmcnt(0)
	v_lshl_add_u64 v[4:5], s[26:27], 0, v[4:5]
	v_and_b32_e32 v0, 0x70, v0
	v_lshlrev_b64 v[2:3], 12, v[2:3]
	v_lshl_add_u64 v[10:11], v[4:5], 0, v[0:1]
	v_lshl_add_u64 v[4:5], v[24:25], 0, s[4:5]
	v_and_b32_e32 v30, 15, v187
	v_lshl_add_u64 v[2:3], s[26:27], 0, v[2:3]
	v_lshlrev_b64 v[4:5], 14, v[4:5]
	v_lshl_add_u64 v[2:3], v[2:3], 0, s[24:25]
	v_lshlrev_b32_e32 v184, 4, v30
	v_lshl_add_u64 v[4:5], s[26:27], 0, v[4:5]
	v_lshl_add_u64 v[2:3], v[2:3], 0, v[184:185]
	v_lshl_add_u64 v[4:5], s[16:17], 1, v[4:5]
	v_lshl_add_u64 v[18:19], v[4:5], 0, v[0:1]
	v_add_co_u32_e32 v4, vcc, s40, v2
	s_and_b32 s4, s57, 7
	s_nop 0
	v_addc_co_u32_e32 v5, vcc, 0, v3, vcc
	v_add_co_u32_e32 v6, vcc, s41, v2
	s_lshl_b32 s4, s4, 2
	s_lshl_b32 s25, s56, 8
	v_addc_co_u32_e32 v7, vcc, 0, v3, vcc
	s_or_b32 s4, s4, 3
	s_add_i32 s25, s25, s29
	v_add_co_u32_e32 v10, vcc, s42, v10
	v_and_b32_e32 v202, 31, v187
	s_add_u32 s16, s16, s25
	v_addc_co_u32_e32 v11, vcc, 0, v11, vcc
	v_or_b32_e32 v28, s16, v202
	v_mov_b64_e32 v[26:27], s[26:27]
	v_add_co_u32_e32 v14, vcc, s43, v18
	v_ashrrev_i32_e32 v31, 5, v187
	s_addc_u32 s17, s17, 0
	v_mad_u64_u32 v[26:27], s[62:63], v28, s37, v[26:27]
	v_addc_co_u32_e32 v15, vcc, 0, v19, vcc
	v_mad_i32_i24 v27, s17, v200, v27
	s_lshl_b32 s62, s58, 1
	s_mov_b32 s63, s5
	v_lshlrev_b32_e32 v188, 3, v31
	v_add_co_u32_e32 v18, vcc, s44, v18
	v_lshl_add_u64 v[26:27], v[26:27], 0, s[62:63]
	v_ashrrev_i32_e32 v189, 31, v188
	global_load_dwordx4 v[2:5], v[4:5], off
	s_nop 0
	global_load_dwordx4 v[6:9], v[6:7], off
	v_addc_co_u32_e32 v19, vcc, 0, v19, vcc
	v_lshl_add_u64 v[26:27], v[188:189], 1, v[26:27]
	global_load_dwordx4 v[10:13], v[10:11], off
	v_lshl_add_u64 v[28:29], v[26:27], 0, s[8:9]
	v_add_co_u32_e32 v26, vcc, s38, v26
	global_load_dwordx4 v[14:17], v[14:15], off
	s_nop 0
	v_addc_co_u32_e32 v27, vcc, 0, v27, vcc
	global_load_dwordx4 v[18:21], v[18:19], off
	s_nop 0
	global_load_dwordx4 v[152:155], v[28:29], off offset:32
	global_load_dwordx4 v[148:151], v[28:29], off offset:64
	global_load_dwordx4 v[144:147], v[28:29], off offset:96
	global_load_dwordx4 v[140:143], v[28:29], off offset:128
	global_load_dwordx4 v[136:139], v[28:29], off offset:160
	global_load_dwordx4 v[132:135], v[28:29], off offset:192
	global_load_dwordx4 v[128:131], v[28:29], off offset:224
	global_load_dwordx4 v[124:127], v[28:29], off offset:256
	global_load_dwordx4 v[120:123], v[28:29], off offset:288
	global_load_dwordx4 v[116:119], v[28:29], off offset:320
	global_load_dwordx4 v[156:159], v[26:27], off
	global_load_dwordx4 v[112:115], v[28:29], off offset:352
	v_mad_u64_u32 v[190:191], s[62:63], v22, s39, v[184:185]
	v_add_u32_e32 v26, 0, v190
	v_mad_u64_u32 v[192:193], s[62:63], v24, s39, v[0:1]
	s_waitcnt vmcnt(16)
	ds_write_b128 v26, v[2:5]
	s_waitcnt vmcnt(15)
	ds_write_b128 v26, v[6:9] offset:12800
	v_add_u32_e32 v2, 0, v192
	v_mul_lo_u32 v3, v24, s45
	s_lshr_b32 s25, s25, 6
	s_waitcnt vmcnt(14)
	ds_write_b128 v2, v[10:13] offset:256
	v_add_u32_e32 v2, v2, v3
	v_sub_u32_e32 v2, v2, v216
	v_add_u32_e32 v203, v192, v3
	v_sub_u32_e32 v203, v203, v216
	v_add_u32_e32 v3, 0x6400, v2
	v_add_u32_e32 v2, 0x8800, v2
	s_add_u32 s18, s18, s59
	s_waitcnt vmcnt(13)
	ds_write2_b64 v3, v[14:15], v[16:17] offset1:2
	s_waitcnt vmcnt(12)
; #define LAS __attribute__((address_space(3)))
; #define A_LOAD(kt) do { const size_t ko = (size_t)(kt) * 64; st0 = *(const u32x4*)(kn_src + ko * 2048); st1 = *(const u32x4*)(kn_src + (ko + 32) * 2048); \
;         st2 = *(const u32x4*)(kr_src + ko * 64); st3 = *(const u32x4*)(v_src + ko); st4 = *(const u32x4*)(v_src + ko + (size_t)64 * 8192); } while (0)
; DI void attn_unit(LAS unsigned char* lds, int wid, int b, int h, int qb) {
;     ...
;     f32x16 o[4];
; #pragma unroll
;     for (int dt = 0; dt < 4; ++dt)
; #pragma unroll
;         for (int i = 0; i < 16; ++i) o[dt][i] = 0.f;
;     float mrow = -__builtin_inff(), lrow = 0.f;
;     const int krow = tid >> 4, kc16 = tid & 15, rrow = tid >> 3, rc8 = tid & 7;
;     const bf16_t* kn_src = KN + ((size_t)b * SEQ + krow) * 2048 + h * 128 + kc16 * 8;
;     const bf16_t* kr_src = KR + ((size_t)b * SEQ + rrow) * 64 + rc8 * 8;
;     const bf16_t* v_src = VT + ((size_t)h * 128 + rrow) * 8192 + (size_t)b * SEQ + rc8 * 8;
;     const int kn_dst = krow * KROW + kc16 * 16, kr_dst = rrow * KROW + 256 + rc8 * 16, v_dst = KBYTES + rrow * VROW + rc8 * 16;
;     u32x4 st0, st1, st2, st3, st4;
;     ...
;     A_LOAD(0); A_WRITE(0); __syncthreads();
;     for (int kt = 0; kt < nkt; ++kt) {
;         const int buf = kt & 1;
;         if (kt + 1 < nkt) A_LOAD(kt + 1);
;         if (kt <= cq) {
;             LAS unsigned char* kb = lds + buf * ABUF; LAS unsigned char* vb = kb + KBYTES;
;             f32x16 s0, s1;
; #pragma unroll
;             for (int i = 0; i < 16; ++i) { s0[i] = 0.f; s1[i] = 0.f; }
;     ...
;             bf16x8 ka[3][2];
;             ka[0][0] = KLD(0, 0); ka[0][1] = KLD(0, 1); ka[1][0] = KLD(1, 0); ka[1][1] = KLD(1, 1);
; #pragma unroll
;             for (int ks = 0; ks < 12; ++ks) {
;                 if (ks + 2 < 12) { ka[(ks + 2) % 3][0] = KLD(ks + 2, 0); ka[(ks + 2) % 3][1] = KLD(ks + 2, 1); }
;                 s0 = __builtin_amdgcn_mfma_f32_32x32x16_bf16(ka[ks % 3][0], qf[ks], s0, 0, 0, 0); s1 = __builtin_amdgcn_mfma_f32_32x32x16_bf16(ka[ks % 3][1], qf[ks], s1, 0, 0, 0);
;                 __builtin_amdgcn_sched_barrier(0); }
	ds_write2_b64 v2, v[18:19], v[20:21] offset1:2
	v_lshlrev_b32_e32 v2, 2, v187
	v_xor_b32_e32 v189, 0x80, v2
	v_lshlrev_b64 v[2:3], 14, v[24:25]
	s_addc_u32 s19, s19, 0
	v_lshl_add_u64 v[2:3], s[18:19], 0, v[2:3]
	v_lshl_add_u64 v[194:195], v[2:3], 0, v[0:1]
	v_lshlrev_b64 v[2:3], 7, v[24:25]
	v_lshl_add_u64 v[2:3], s[20:21], 0, v[2:3]
	s_add_u32 s18, s60, s22
	v_lshl_add_u64 v[196:197], v[2:3], 0, v[0:1]
	v_lshlrev_b64 v[2:3], 12, v[22:23]
	s_addc_u32 s19, 0, s23
	v_lshl_add_u64 v[2:3], s[18:19], 0, v[2:3]
	v_mov_b32_e32 v14, v1
	v_mov_b32_e32 v15, v1
	v_lshlrev_b32_e32 v186, 3, v30
	v_lshlrev_b32_e32 v204, 4, v31
	v_lshl_add_u64 v[198:199], v[2:3], 0, v[184:185]
	v_mov_b32_e32 v0, v1
	v_mov_b32_e32 v2, v1
	v_mov_b32_e32 v3, v1
	v_mov_b32_e32 v4, v1
	v_mov_b32_e32 v5, v1
	v_mov_b32_e32 v6, v1
	v_mov_b32_e32 v7, v1
	v_mov_b32_e32 v8, v1
	v_mov_b32_e32 v9, v1
	v_mov_b32_e32 v10, v1
	v_mov_b32_e32 v11, v1
	v_mov_b32_e32 v12, v1
	v_mov_b32_e32 v13, v1
	v_mov_b64_e32 v[30:31], v[14:15]
	v_mov_b64_e32 v[46:47], v[14:15]
	v_mov_b64_e32 v[62:63], v[14:15]
	v_mov_b64_e32 v[78:79], v[14:15]
	s_mov_b32 s57, 0
	v_mul_u32_u24_e32 v193, 0x190, v202
	v_mul_u32_u24_e32 v191, 0x90, v202
	v_mov_b32_e32 v185, 0
	v_mov_b64_e32 v[28:29], v[12:13]
	v_mov_b64_e32 v[26:27], v[10:11]
	v_mov_b64_e32 v[24:25], v[8:9]
	v_mov_b64_e32 v[22:23], v[6:7]
	v_mov_b64_e32 v[20:21], v[4:5]
	v_mov_b64_e32 v[18:19], v[2:3]
	v_mov_b64_e32 v[16:17], v[0:1]
	v_mov_b64_e32 v[44:45], v[12:13]
	v_mov_b64_e32 v[42:43], v[10:11]
	v_mov_b64_e32 v[40:41], v[8:9]
	v_mov_b64_e32 v[38:39], v[6:7]
	v_mov_b64_e32 v[36:37], v[4:5]
	v_mov_b64_e32 v[34:35], v[2:3]
	v_mov_b64_e32 v[32:33], v[0:1]
	v_mov_b64_e32 v[60:61], v[12:13]
	v_mov_b64_e32 v[58:59], v[10:11]
	v_mov_b64_e32 v[56:57], v[8:9]
	v_mov_b64_e32 v[54:55], v[6:7]
	v_mov_b64_e32 v[52:53], v[4:5]
	v_mov_b64_e32 v[50:51], v[2:3]
	v_mov_b64_e32 v[48:49], v[0:1]
	v_mov_b64_e32 v[76:77], v[12:13]
	v_mov_b64_e32 v[74:75], v[10:11]
	v_mov_b64_e32 v[72:73], v[8:9]
	v_mov_b64_e32 v[70:71], v[6:7]
	v_mov_b64_e32 v[68:69], v[4:5]
	v_mov_b64_e32 v[66:67], v[2:3]
	v_mov_b64_e32 v[64:65], v[0:1]
	s_waitcnt lgkmcnt(0)
	s_barrier
.LBB0_1091:
	v_lshl_add_u64 v[2:3], s[26:27], 0, v[198:199]
	v_add_co_u32_e32 v4, vcc, 0x11140000, v2
	v_lshl_add_u64 v[14:15], s[26:27], 0, v[194:195]
	s_nop 0
	v_addc_co_u32_e32 v5, vcc, 0, v3, vcc
	v_add_co_u32_e32 v6, vcc, 0x11160000, v2
	v_lshl_add_u64 v[10:11], s[26:27], 0, v[196:197]
	s_nop 0
	v_addc_co_u32_e32 v7, vcc, 0, v3, vcc
	v_add_co_u32_e32 v80, vcc, 0x13100000, v14
	global_load_dwordx4 v[2:5], v[4:5], off
	s_nop 0
	global_load_dwordx4 v[6:9], v[6:7], off
	v_addc_co_u32_e32 v81, vcc, 0, v15, vcc
	v_add_co_u32_e32 v14, vcc, 0x13200000, v14
	global_load_dwordx4 v[10:13], v[10:11], off
	s_nop 0
	global_load_dwordx4 v[160:163], v[80:81], off offset:128
	v_addc_co_u32_e32 v15, vcc, 0, v15, vcc
	global_load_dwordx4 v[164:167], v[14:15], off offset:128
	s_and_b32 s18, s57, 1
	s_cmp_gt_u32 s57, s25
	s_cbranch_scc1 .LBB0_1095
	s_mul_i32 s19, s18, 0xac00
	s_add_i32 s19, s19, 0
	v_add3_u32 v0, s19, v193, v204
	ds_read_b128 v[80:83], v0
	ds_read_b128 v[168:171], v0 offset:32
	ds_read_b128 v[96:99], v0 offset:12800
	ds_read_b128 v[174:177], v0 offset:64
	ds_read_b128 v[178:181], v0 offset:12832
	ds_read_b128 v[206:209], v0 offset:12864
	s_waitcnt vmcnt(6) lgkmcnt(3)
	v_mfma_f32_32x32x16_bf16 v[96:111], v[96:99], v[156:159], 0
	v_mfma_f32_32x32x16_bf16 v[80:95], v[80:83], v[156:159], 0
	v_mfma_f32_32x32x16_bf16 v[80:95], v[168:171], v[152:155], v[80:95]
	ds_read_b128 v[168:171], v0 offset:96
	ds_read_b128 v[210:213], v0 offset:12896
	s_waitcnt lgkmcnt(3)
	v_mfma_f32_32x32x16_bf16 v[96:111], v[178:181], v[152:155], v[96:111]
	v_mfma_f32_32x32x16_bf16 v[80:95], v[174:177], v[148:151], v[80:95]
	ds_read_b128 v[174:177], v0 offset:128
	ds_read_b128 v[178:181], v0 offset:12928
	s_waitcnt lgkmcnt(4)
	v_mfma_f32_32x32x16_bf16 v[96:111], v[206:209], v[148:151], v[96:111]
	s_waitcnt lgkmcnt(3)
	v_mfma_f32_32x32x16_bf16 v[80:95], v[168:171], v[144:147], v[80:95]
	ds_read_b128 v[168:171], v0 offset:160
	ds_read_b128 v[206:209], v0 offset:12960
	s_waitcnt lgkmcnt(4)
	v_mfma_f32_32x32x16_bf16 v[96:111], v[210:213], v[144:147], v[96:111]
	s_waitcnt lgkmcnt(3)
	v_mfma_f32_32x32x16_bf16 v[80:95], v[174:177], v[140:143], v[80:95]
	ds_read_b128 v[174:177], v0 offset:192
	ds_read_b128 v[210:213], v0 offset:12992
	s_waitcnt lgkmcnt(4)
	v_mfma_f32_32x32x16_bf16 v[96:111], v[178:181], v[140:143], v[96:111]
	s_waitcnt lgkmcnt(3)
	v_mfma_f32_32x32x16_bf16 v[80:95], v[168:171], v[136:139], v[80:95]
	ds_read_b128 v[168:171], v0 offset:224
	ds_read_b128 v[178:181], v0 offset:13024
	s_waitcnt lgkmcnt(4)
	v_mfma_f32_32x32x16_bf16 v[96:111], v[206:209], v[136:139], v[96:111]
	s_waitcnt lgkmcnt(3)
	v_mfma_f32_32x32x16_bf16 v[80:95], v[174:177], v[132:135], v[80:95]
	ds_read_b128 v[174:177], v0 offset:256
	ds_read_b128 v[206:209], v0 offset:13056
	s_waitcnt lgkmcnt(4)
	v_mfma_f32_32x32x16_bf16 v[96:111], v[210:213], v[132:135], v[96:111]
	s_waitcnt lgkmcnt(3)
	v_mfma_f32_32x32x16_bf16 v[80:95], v[168:171], v[128:131], v[80:95]
	ds_read_b128 v[168:171], v0 offset:288
	ds_read_b128 v[210:213], v0 offset:13088
	s_waitcnt lgkmcnt(4)
	v_mfma_f32_32x32x16_bf16 v[96:111], v[178:181], v[128:131], v[96:111]
	s_waitcnt lgkmcnt(3)
	v_mfma_f32_32x32x16_bf16 v[80:95], v[174:177], v[124:127], v[80:95]
	ds_read_b128 v[174:177], v0 offset:320
	ds_read_b128 v[178:181], v0 offset:13120
	s_waitcnt lgkmcnt(4)
	v_mfma_f32_32x32x16_bf16 v[96:111], v[206:209], v[124:127], v[96:111]
	s_waitcnt lgkmcnt(3)
; DI float shfl_xor_l(float v, int lane, int m) { return __int_as_float(__builtin_amdgcn_ds_bpermute((lane ^ m) << 2, __float_as_int(v))); }
; #define VLD(dst, j, dt) do { LAS unsigned char* va_ = vb + (32 * (dt) + n) * VROW + (16 * (j) + 4 * g) * 2; const u32x2 lo_ = *(const LAS u32x2*)(va_), hi_ = *(const LAS u32x2*)(va_ + 16); dst = (u32x4){lo_.x, lo_.y, hi_.x, hi_.y}; } while (0)
; DI void attn_unit(LAS unsigned char* lds, int wid, int b, int h, int qb) {
;     ...
;             for (int ks = 0; ks < 12; ++ks) {
;                 if (ks + 2 < 12) { ka[(ks + 2) % 3][0] = KLD(ks + 2, 0); ka[(ks + 2) % 3][1] = KLD(ks + 2, 1); }
;                 s0 = __builtin_amdgcn_mfma_f32_32x32x16_bf16(ka[ks % 3][0], qf[ks], s0, 0, 0, 0); s1 = __builtin_amdgcn_mfma_f32_32x32x16_bf16(ka[ks % 3][1], qf[ks], s1, 0, 0, 0);
;                 __builtin_amdgcn_sched_barrier(0); }
;             u32x4 vf[2][4];
; #pragma unroll
;             for (int dt = 0; dt < 4; ++dt) VLD(vf[0][dt], 0, dt);
;             float mx = s0[0];
; #pragma unroll
;             for (int i = 1; i < 16; ++i) mx = fmaxf(mx, s0[i]);
; #pragma unroll
;             for (int i = 0; i < 16; ++i) mx = fmaxf(mx, s1[i]);
;             mx = fmaxf(mx, shfl_xor_l(mx, lane, 32));
;             const float mnew = fmaxf(mrow, mx), alpha = __builtin_amdgcn_exp2f(mrow - mnew); mrow = mnew;
;             float ls = 0.f;
; #pragma unroll
;             for (int i = 0; i < 16; ++i) { s0[i] = __builtin_amdgcn_exp2f(s0[i] - mnew); s1[i] = __builtin_amdgcn_exp2f(s1[i] - mnew); ls += s0[i] + s1[i]; }
;             lrow = lrow * alpha + ls;
;             if (__builtin_amdgcn_ballot_w64(alpha != 1.f) != 0ull) {
; #pragma unroll
;                 for (int dt = 0; dt < 4; ++dt)
; #pragma unroll
;                     for (int i = 0; i < 16; ++i) o[dt][i] *= alpha;
;             }
	v_mfma_f32_32x32x16_bf16 v[80:95], v[168:171], v[120:123], v[80:95]
	ds_read_b128 v[168:171], v0 offset:352
	ds_read_b128 v[206:209], v0 offset:13152
	s_waitcnt lgkmcnt(4)
	v_mfma_f32_32x32x16_bf16 v[96:111], v[210:213], v[120:123], v[96:111]
	s_waitcnt lgkmcnt(3)
	v_mfma_f32_32x32x16_bf16 v[80:95], v[174:177], v[116:119], v[80:95]
	s_waitcnt lgkmcnt(2)
	v_mfma_f32_32x32x16_bf16 v[96:111], v[178:181], v[116:119], v[96:111]
	s_waitcnt vmcnt(5) lgkmcnt(1)
	v_mfma_f32_32x32x16_bf16 v[80:95], v[168:171], v[112:115], v[80:95]
	v_add_u32_e32 v0, s19, v188
	v_add_u32_e32 v173, v0, v191
	v_add_u32_e32 v173, v173, v188
	v_add_u32_e32 v15, 0x6000, v173
	v_add_u32_e32 v205, 0x7000, v173
	ds_read_b128 v[168:171], v15 offset:1024
	ds_read_b128 v[180:183], v205 offset:1536
	s_nop 5
	v_max_f32_e32 v0, v81, v81
	v_max_f32_e32 v14, v80, v80
	v_max_f32_e32 v0, v14, v0
	s_waitcnt lgkmcnt(2)
	v_mfma_f32_32x32x16_bf16 v[96:111], v[206:209], v[112:115], v[96:111]
	v_max3_f32 v0, v0, v82, v83
	v_max3_f32 v0, v0, v84, v85
	v_max3_f32 v0, v0, v86, v87
	v_max3_f32 v0, v0, v88, v89
	v_max3_f32 v0, v0, v90, v91
	v_max3_f32 v0, v0, v92, v93
	v_max3_f32 v0, v0, v94, v95
	s_nop 4
	v_max3_f32 v0, v0, v96, v97
	v_max3_f32 v0, v0, v98, v99
	v_max3_f32 v0, v0, v100, v101
	v_max3_f32 v0, v0, v102, v103
	v_max3_f32 v0, v0, v104, v105
	v_max3_f32 v0, v0, v106, v107
	v_max3_f32 v0, v0, v108, v109
	v_max3_f32 v0, v0, v110, v111
	ds_bpermute_b32 v14, v189, v0
	v_add_u32_e32 v206, 0x8000, v173
	v_add_u32_e32 v207, 0x9000, v173
	ds_read_b128 v[176:179], v206 offset:2048
	s_waitcnt lgkmcnt(1)
	v_max3_f32 v14, v172, v0, v14
	v_sub_f32_e32 v0, v172, v14
	v_exp_f32_e32 v0, v0
	ds_read_b128 v[172:175], v207 offset:2560
	v_cmp_neq_f32_e32 vcc, 1.0, v0
	s_cbranch_vccz .LBB0_1094
	v_pk_mul_f32 v[78:79], v[78:79], v[0:1] op_sel_hi:[1,0]
	v_pk_mul_f32 v[76:77], v[76:77], v[0:1] op_sel_hi:[1,0]
	v_pk_mul_f32 v[74:75], v[74:75], v[0:1] op_sel_hi:[1,0]
	v_pk_mul_f32 v[72:73], v[72:73], v[0:1] op_sel_hi:[1,0]
	v_pk_mul_f32 v[70:71], v[70:71], v[0:1] op_sel_hi:[1,0]
	v_pk_mul_f32 v[68:69], v[68:69], v[0:1] op_sel_hi:[1,0]
	v_pk_mul_f32 v[66:67], v[66:67], v[0:1] op_sel_hi:[1,0]
	v_pk_mul_f32 v[64:65], v[64:65], v[0:1] op_sel_hi:[1,0]
	v_pk_mul_f32 v[62:63], v[62:63], v[0:1] op_sel_hi:[1,0]
	v_pk_mul_f32 v[60:61], v[60:61], v[0:1] op_sel_hi:[1,0]
	v_pk_mul_f32 v[58:59], v[58:59], v[0:1] op_sel_hi:[1,0]
	v_pk_mul_f32 v[56:57], v[56:57], v[0:1] op_sel_hi:[1,0]
	v_pk_mul_f32 v[54:55], v[54:55], v[0:1] op_sel_hi:[1,0]
	v_pk_mul_f32 v[52:53], v[52:53], v[0:1] op_sel_hi:[1,0]
	v_pk_mul_f32 v[50:51], v[50:51], v[0:1] op_sel_hi:[1,0]
	v_pk_mul_f32 v[48:49], v[48:49], v[0:1] op_sel_hi:[1,0]
	v_pk_mul_f32 v[46:47], v[46:47], v[0:1] op_sel_hi:[1,0]
	v_pk_mul_f32 v[44:45], v[44:45], v[0:1] op_sel_hi:[1,0]
	v_pk_mul_f32 v[42:43], v[42:43], v[0:1] op_sel_hi:[1,0]
	v_pk_mul_f32 v[40:41], v[40:41], v[0:1] op_sel_hi:[1,0]
	v_pk_mul_f32 v[38:39], v[38:39], v[0:1] op_sel_hi:[1,0]
	v_pk_mul_f32 v[36:37], v[36:37], v[0:1] op_sel_hi:[1,0]
	v_pk_mul_f32 v[34:35], v[34:35], v[0:1] op_sel_hi:[1,0]
	v_pk_mul_f32 v[32:33], v[32:33], v[0:1] op_sel_hi:[1,0]
	v_pk_mul_f32 v[30:31], v[30:31], v[0:1] op_sel_hi:[1,0]
	v_pk_mul_f32 v[28:29], v[28:29], v[0:1] op_sel_hi:[1,0]
	v_pk_mul_f32 v[26:27], v[26:27], v[0:1] op_sel_hi:[1,0]
	v_pk_mul_f32 v[24:25], v[24:25], v[0:1] op_sel_hi:[1,0]
	v_pk_mul_f32 v[22:23], v[22:23], v[0:1] op_sel_hi:[1,0]
	v_pk_mul_f32 v[20:21], v[20:21], v[0:1] op_sel_hi:[1,0]
	v_pk_mul_f32 v[18:19], v[18:19], v[0:1] op_sel_hi:[1,0]
	v_pk_mul_f32 v[16:17], v[16:17], v[0:1] op_sel_hi:[1,0]
; DI unsigned pk2(float a, float b) { f32x2 f = {a, b}; bf16v2 r = __builtin_convertvector(f, bf16v2); return __builtin_bit_cast(unsigned, r); }
; #define VLD(dst, j, dt) do { LAS unsigned char* va_ = vb + (32 * (dt) + n) * VROW + (16 * (j) + 4 * g) * 2; const u32x2 lo_ = *(const LAS u32x2*)(va_), hi_ = *(const LAS u32x2*)(va_ + 16); dst = (u32x4){lo_.x, lo_.y, hi_.x, hi_.y}; } while (0)
; DI void attn_unit(LAS unsigned char* lds, int wid, int b, int h, int qb) {
;     ...
;             float ls = 0.f;
; #pragma unroll
;             for (int i = 0; i < 16; ++i) { s0[i] = __builtin_amdgcn_exp2f(s0[i] - mnew); s1[i] = __builtin_amdgcn_exp2f(s1[i] - mnew); ls += s0[i] + s1[i]; }
;             lrow = lrow * alpha + ls;
;             if (__builtin_amdgcn_ballot_w64(alpha != 1.f) != 0ull) {
; #pragma unroll
;                 for (int dt = 0; dt < 4; ++dt)
; #pragma unroll
;                     for (int i = 0; i < 16; ++i) o[dt][i] *= alpha;
;             }
;             bf16x8 pf[4];
; #pragma unroll
;             for (int jj = 0; jj < 2; ++jj) { u32x4 w0, w1;
;                 w0.x = pk2(s0[8 * jj + 0], s0[8 * jj + 1]); w0.y = pk2(s0[8 * jj + 2], s0[8 * jj + 3]); w0.z = pk2(s0[8 * jj + 4], s0[8 * jj + 5]); w0.w = pk2(s0[8 * jj + 6], s0[8 * jj + 7]);
;                 w1.x = pk2(s1[8 * jj + 0], s1[8 * jj + 1]); w1.y = pk2(s1[8 * jj + 2], s1[8 * jj + 3]); w1.z = pk2(s1[8 * jj + 4], s1[8 * jj + 5]); w1.w = pk2(s1[8 * jj + 6], s1[8 * jj + 7]);
;                 pf[jj] = __builtin_bit_cast(bf16x8, w0); pf[2 + jj] = __builtin_bit_cast(bf16x8, w1); }
; #pragma unroll
;             for (int j = 0; j < 4; ++j) {
;                 if (j < 3) {
; #pragma unroll
;                     for (int dt = 0; dt < 4; ++dt) VLD(vf[(j + 1) & 1][dt], j + 1, dt);
;                 }
; #pragma unroll
;                 for (int dt = 0; dt < 4; ++dt) o[dt] = __builtin_amdgcn_mfma_f32_32x32x16_bf16(__builtin_bit_cast(bf16x8, vf[j & 1][dt]), pf[j], o[dt], 0, 0, 0);
;                 __builtin_amdgcn_sched_barrier(0); }
.LBB0_1094:
	v_sub_f32_e32 v80, v80, v14
	v_sub_f32_e32 v96, v96, v14
	v_exp_f32_e32 v80, v80
	v_exp_f32_e32 v96, v96
	v_sub_f32_e32 v81, v81, v14
	v_sub_f32_e32 v97, v97, v14
	v_exp_f32_e32 v81, v81
	v_exp_f32_e32 v97, v97
	v_sub_f32_e32 v82, v82, v14
	v_sub_f32_e32 v98, v98, v14
	v_exp_f32_e32 v82, v82
	v_exp_f32_e32 v98, v98
	v_sub_f32_e32 v83, v83, v14
	v_sub_f32_e32 v99, v99, v14
	v_exp_f32_e32 v83, v83
	v_exp_f32_e32 v99, v99
	v_sub_f32_e32 v84, v84, v14
	v_sub_f32_e32 v100, v100, v14
	v_add_f32_e32 v208, v96, v80
	v_exp_f32_e32 v84, v84
	v_exp_f32_e32 v100, v100
	v_sub_f32_e32 v85, v85, v14
	v_sub_f32_e32 v101, v101, v14
	v_add_f32_e32 v208, 0, v208
	v_add_f32_e32 v209, v97, v81
	v_exp_f32_e32 v85, v85
	v_exp_f32_e32 v101, v101
	v_sub_f32_e32 v86, v86, v14
	v_sub_f32_e32 v102, v102, v14
	v_add_f32_e32 v208, v209, v208
	v_add_f32_e32 v209, v98, v82
	v_exp_f32_e32 v86, v86
	v_exp_f32_e32 v102, v102
	v_sub_f32_e32 v87, v87, v14
	v_sub_f32_e32 v103, v103, v14
	v_add_f32_e32 v208, v209, v208
	v_add_f32_e32 v209, v99, v83
	v_exp_f32_e32 v87, v87
	v_exp_f32_e32 v103, v103
	v_sub_f32_e32 v88, v88, v14
	v_sub_f32_e32 v104, v104, v14
	v_add_f32_e32 v208, v209, v208
	v_add_f32_e32 v209, v100, v84
	v_exp_f32_e32 v88, v88
	v_exp_f32_e32 v104, v104
	v_sub_f32_e32 v89, v89, v14
	v_sub_f32_e32 v105, v105, v14
	v_add_f32_e32 v208, v209, v208
	v_add_f32_e32 v209, v101, v85
	v_exp_f32_e32 v89, v89
	v_exp_f32_e32 v105, v105
	v_sub_f32_e32 v90, v90, v14
	v_sub_f32_e32 v106, v106, v14
	v_add_f32_e32 v208, v209, v208
	v_add_f32_e32 v209, v102, v86
	v_exp_f32_e32 v90, v90
	v_exp_f32_e32 v106, v106
	v_sub_f32_e32 v91, v91, v14
	v_sub_f32_e32 v107, v107, v14
	v_add_f32_e32 v208, v209, v208
	v_add_f32_e32 v209, v103, v87
	v_exp_f32_e32 v91, v91
	v_exp_f32_e32 v107, v107
	v_sub_f32_e32 v92, v92, v14
	v_sub_f32_e32 v108, v108, v14
	v_add_f32_e32 v208, v209, v208
	v_add_f32_e32 v209, v104, v88
	v_exp_f32_e32 v92, v92
	v_exp_f32_e32 v108, v108
	v_sub_f32_e32 v93, v93, v14
	v_sub_f32_e32 v109, v109, v14
	v_add_f32_e32 v208, v209, v208
	v_add_f32_e32 v209, v105, v89
	v_exp_f32_e32 v93, v93
	v_exp_f32_e32 v109, v109
	v_sub_f32_e32 v94, v94, v14
	v_sub_f32_e32 v110, v110, v14
	v_add_f32_e32 v208, v209, v208
	v_add_f32_e32 v209, v106, v90
	v_exp_f32_e32 v94, v94
	v_exp_f32_e32 v110, v110
	v_sub_f32_e32 v95, v95, v14
	v_sub_f32_e32 v111, v111, v14
	v_add_f32_e32 v208, v209, v208
	v_add_f32_e32 v209, v107, v91
	v_exp_f32_e32 v95, v95
	v_exp_f32_e32 v111, v111
	v_add_f32_e32 v208, v209, v208
	v_add_f32_e32 v209, v108, v92
	v_add_f32_e32 v208, v209, v208
	v_add_f32_e32 v209, v109, v93
	v_add_f32_e32 v208, v209, v208
	v_cvt_pk_bf16_f32 v80, v80, v81
	v_cvt_pk_bf16_f32 v81, v82, v83
	v_cvt_pk_bf16_f32 v82, v84, v85
	v_cvt_pk_bf16_f32 v83, v86, v87
	v_add_f32_e32 v84, v110, v94
	v_add_f32_e32 v84, v84, v208
	v_mfma_f32_32x32x16_bf16 v[64:79], v[168:171], v[80:83], v[64:79]
	v_add_f32_e32 v85, v111, v95
	v_add_f32_e32 v168, v85, v84
	v_cvt_pk_bf16_f32 v84, v96, v97
	v_cvt_pk_bf16_f32 v85, v98, v99
	v_cvt_pk_bf16_f32 v86, v100, v101
	v_cvt_pk_bf16_f32 v87, v102, v103
	v_cvt_pk_bf16_f32 v88, v88, v89
	v_mfma_f32_32x32x16_bf16 v[48:63], v[180:183], v[80:83], v[48:63]
	v_cvt_pk_bf16_f32 v89, v90, v91
	v_cvt_pk_bf16_f32 v90, v92, v93
	v_cvt_pk_bf16_f32 v91, v94, v95
	v_cvt_pk_bf16_f32 v92, v104, v105
	v_cvt_pk_bf16_f32 v93, v106, v107
	v_cvt_pk_bf16_f32 v94, v108, v109
	v_cvt_pk_bf16_f32 v95, v110, v111
	s_waitcnt lgkmcnt(1)
	v_mfma_f32_32x32x16_bf16 v[32:47], v[176:179], v[80:83], v[32:47]
	ds_read_b128 v[96:99], v15 offset:1056
	ds_read_b128 v[100:103], v205 offset:1568
	ds_read_b128 v[104:107], v206 offset:2080
	ds_read_b128 v[108:111], v207 offset:2592
	v_fmac_f32_e32 v168, v185, v0
	s_waitcnt lgkmcnt(4)
	v_mfma_f32_32x32x16_bf16 v[16:31], v[172:175], v[80:83], v[16:31]
	s_waitcnt lgkmcnt(3)
	v_mfma_f32_32x32x16_bf16 v[64:79], v[96:99], v[88:91], v[64:79]
	s_waitcnt lgkmcnt(2)
	v_mfma_f32_32x32x16_bf16 v[48:63], v[100:103], v[88:91], v[48:63]
	s_waitcnt lgkmcnt(1)
	v_mfma_f32_32x32x16_bf16 v[32:47], v[104:107], v[88:91], v[32:47]
	ds_read_b128 v[80:83], v15 offset:1088
	ds_read_b128 v[96:99], v205 offset:1600
	ds_read_b128 v[100:103], v206 offset:2112
	ds_read_b128 v[104:107], v207 offset:2624
	s_waitcnt lgkmcnt(4)
	v_mfma_f32_32x32x16_bf16 v[16:31], v[108:111], v[88:91], v[16:31]
	s_waitcnt lgkmcnt(3)
	v_mfma_f32_32x32x16_bf16 v[64:79], v[80:83], v[84:87], v[64:79]
	s_waitcnt lgkmcnt(2)
	v_mfma_f32_32x32x16_bf16 v[48:63], v[96:99], v[84:87], v[48:63]
	s_waitcnt lgkmcnt(1)
	v_mfma_f32_32x32x16_bf16 v[32:47], v[100:103], v[84:87], v[32:47]
	ds_read_b128 v[80:83], v15 offset:1120
	ds_read_b128 v[88:91], v205 offset:1632
	ds_read_b128 v[96:99], v206 offset:2144
	ds_read_b128 v[100:103], v207 offset:2656
	s_waitcnt lgkmcnt(4)
	v_mfma_f32_32x32x16_bf16 v[16:31], v[104:107], v[84:87], v[16:31]
	s_waitcnt lgkmcnt(3)
	v_mfma_f32_32x32x16_bf16 v[64:79], v[80:83], v[92:95], v[64:79]
	s_waitcnt lgkmcnt(2)
	v_mfma_f32_32x32x16_bf16 v[48:63], v[88:91], v[92:95], v[48:63]
	s_waitcnt lgkmcnt(1)
	v_mfma_f32_32x32x16_bf16 v[32:47], v[96:99], v[92:95], v[32:47]
	s_waitcnt lgkmcnt(0)
	v_mfma_f32_32x32x16_bf16 v[16:31], v[100:103], v[92:95], v[16:31]
	v_mov_b32_e32 v185, v168
	s_branch .LBB0_1096

; #define LAS __attribute__((address_space(3)))
; DI float shfl_xor_l(float v, int lane, int m) { return __int_as_float(__builtin_amdgcn_ds_bpermute((lane ^ m) << 2, __float_as_int(v))); }
; #define VLD(dst, j, dt) do { LAS unsigned char* va_ = vb + (32 * (dt) + n) * VROW + (16 * (j) + 4 * g) * 2; const u32x2 lo_ = *(const LAS u32x2*)(va_), hi_ = *(const LAS u32x2*)(va_ + 16); dst = (u32x4){lo_.x, lo_.y, hi_.x, hi_.y}; } while (0)
; DI void attn_unit(LAS unsigned char* lds, int wid, int b, int h, int qb) {
;     ...
;         if (kt <= cq) {
;             LAS unsigned char* kb = lds + buf * ABUF; LAS unsigned char* vb = kb + KBYTES;
;             f32x16 s0, s1;
; #pragma unroll
;             for (int i = 0; i < 16; ++i) { s0[i] = 0.f; s1[i] = 0.f; }
;     ...
;             bf16x8 ka[3][2];
;             ka[0][0] = KLD(0, 0); ka[0][1] = KLD(0, 1); ka[1][0] = KLD(1, 0); ka[1][1] = KLD(1, 1);
; #pragma unroll
;             for (int ks = 0; ks < 12; ++ks) {
;                 if (ks + 2 < 12) { ka[(ks + 2) % 3][0] = KLD(ks + 2, 0); ka[(ks + 2) % 3][1] = KLD(ks + 2, 1); }
;                 s0 = __builtin_amdgcn_mfma_f32_32x32x16_bf16(ka[ks % 3][0], qf[ks], s0, 0, 0, 0); s1 = __builtin_amdgcn_mfma_f32_32x32x16_bf16(ka[ks % 3][1], qf[ks], s1, 0, 0, 0);
;                 __builtin_amdgcn_sched_barrier(0); }
;             u32x4 vf[2][4];
; #pragma unroll
;             for (int dt = 0; dt < 4; ++dt) VLD(vf[0][dt], 0, dt);
;             float mx = s0[0];
; #pragma unroll
;             for (int i = 1; i < 16; ++i) mx = fmaxf(mx, s0[i]);
; #pragma unroll
;             for (int i = 0; i < 16; ++i) mx = fmaxf(mx, s1[i]);
;             mx = fmaxf(mx, shfl_xor_l(mx, lane, 32));
;             const float mnew = fmaxf(mrow, mx), alpha = __builtin_amdgcn_exp2f(mrow - mnew); mrow = mnew;
;             float ls = 0.f;
; #pragma unroll
;             for (int i = 0; i < 16; ++i) { s0[i] = __builtin_amdgcn_exp2f(s0[i] - mnew); s1[i] = __builtin_amdgcn_exp2f(s1[i] - mnew); ls += s0[i] + s1[i]; }
;             lrow = lrow * alpha + ls;
;             if (__builtin_amdgcn_ballot_w64(alpha != 1.f) != 0ull) {
; #pragma unroll
;                 for (int dt = 0; dt < 4; ++dt)
; #pragma unroll
;                     for (int i = 0; i < 16; ++i) o[dt][i] *= alpha;
;             }
;     ...
;         if (kt + 1 < nkt) A_WRITE(buf ^ 1);
;         __syncthreads();
.LBB0_1096:
	s_xor_b32 s18, s18, 1
	s_mul_i32 s18, s18, 0xac00
	s_add_i32 s18, s18, 0
	v_add_u32_e32 v0, s18, v190
	s_waitcnt vmcnt(4)
	ds_write_b128 v0, v[2:5]
	s_waitcnt vmcnt(3)
	ds_write_b128 v0, v[6:9] offset:12800
	v_add_u32_e32 v0, s18, v192
	s_add_i32 s57, s57, 1
	s_waitcnt vmcnt(2)
	ds_write_b128 v0, v[10:13] offset:256
	v_add_u32_e32 v0, s18, v203
	v_add_u32_e32 v2, 0x6400, v0
	v_add_u32_e32 v0, 0x8800, v0
	v_lshl_add_u64 v[194:195], v[194:195], 0, s[10:11]
	v_lshl_add_u64 v[196:197], v[196:197], 0, s[12:13]
	s_cmp_eq_u32 s4, s57
	v_lshl_add_u64 v[198:199], v[198:199], 0, s[14:15]
	s_waitcnt vmcnt(1)
	ds_write2_b64 v2, v[160:161], v[162:163] offset1:2
	s_waitcnt vmcnt(0)
	ds_write2_b64 v0, v[164:165], v[166:167] offset1:2
	s_waitcnt lgkmcnt(0)
	s_barrier
	s_cbranch_scc1 .LBB0_1098
	v_mov_b32_e32 v172, v14
	s_branch .LBB0_1091
.LBB0_1098:
	s_lshl_b32 s18, s56, 2
	s_or_b32 s18, s18, 2
	s_cmp_ge_u32 s18, s25
	s_cbranch_scc1 .LBB0_1077
	s_bitcmp1_b32 s4, 0
	s_cselect_b32 s4, 0xac00, 0
	s_add_i32 s4, s4, 0
	v_add3_u32 v0, s4, v193, v204
	ds_read_b128 v[2:5], v0
	ds_read_b128 v[6:9], v0 offset:32
	s_waitcnt lgkmcnt(1)
	v_mfma_f32_32x32x16_bf16 v[80:95], v[2:5], v[156:159], 0
	ds_read_b128 v[2:5], v0 offset:12800
	ds_read_b128 v[10:13], v0 offset:64
	ds_read_b128 v[160:163], v0 offset:12832
	ds_read_b128 v[164:167], v0 offset:12864
	s_waitcnt lgkmcnt(3)
	v_mfma_f32_32x32x16_bf16 v[96:111], v[2:5], v[156:159], 0
	v_mfma_f32_32x32x16_bf16 v[80:95], v[6:9], v[152:155], v[80:95]
	ds_read_b128 v[2:5], v0 offset:96
	ds_read_b128 v[6:9], v0 offset:12896
	s_waitcnt lgkmcnt(3)
	v_mfma_f32_32x32x16_bf16 v[96:111], v[160:163], v[152:155], v[96:111]
	v_mfma_f32_32x32x16_bf16 v[80:95], v[10:13], v[148:151], v[80:95]
	ds_read_b128 v[10:13], v0 offset:128
	ds_read_b128 v[152:155], v0 offset:12928
	s_waitcnt lgkmcnt(4)
	v_mfma_f32_32x32x16_bf16 v[96:111], v[164:167], v[148:151], v[96:111]
	s_waitcnt lgkmcnt(3)
	v_mfma_f32_32x32x16_bf16 v[80:95], v[2:5], v[144:147], v[80:95]
	ds_read_b128 v[2:5], v0 offset:160
	ds_read_b128 v[148:151], v0 offset:12960
	s_waitcnt lgkmcnt(4)
	v_mfma_f32_32x32x16_bf16 v[96:111], v[6:9], v[144:147], v[96:111]
	s_waitcnt lgkmcnt(3)
	v_mfma_f32_32x32x16_bf16 v[80:95], v[10:13], v[140:143], v[80:95]
	ds_read_b128 v[6:9], v0 offset:192
	ds_read_b128 v[10:13], v0 offset:12992
	s_waitcnt lgkmcnt(4)
	v_mfma_f32_32x32x16_bf16 v[96:111], v[152:155], v[140:143], v[96:111]
	s_waitcnt lgkmcnt(3)
	v_mfma_f32_32x32x16_bf16 v[80:95], v[2:5], v[136:139], v[80:95]
	ds_read_b128 v[2:5], v0 offset:224
	ds_read_b128 v[140:143], v0 offset:13024
	s_waitcnt lgkmcnt(4)
	v_mfma_f32_32x32x16_bf16 v[96:111], v[148:151], v[136:139], v[96:111]
	s_waitcnt lgkmcnt(3)
	v_mfma_f32_32x32x16_bf16 v[80:95], v[6:9], v[132:135], v[80:95]
	ds_read_b128 v[6:9], v0 offset:256
	ds_read_b128 v[136:139], v0 offset:13056
	s_waitcnt lgkmcnt(4)
	v_mfma_f32_32x32x16_bf16 v[96:111], v[10:13], v[132:135], v[96:111]
	s_waitcnt lgkmcnt(3)
	v_mfma_f32_32x32x16_bf16 v[80:95], v[2:5], v[128:131], v[80:95]
	ds_read_b128 v[2:5], v0 offset:288
	ds_read_b128 v[10:13], v0 offset:13088
	s_waitcnt lgkmcnt(4)
	v_mfma_f32_32x32x16_bf16 v[96:111], v[140:143], v[128:131], v[96:111]
	s_waitcnt lgkmcnt(3)
	v_mfma_f32_32x32x16_bf16 v[80:95], v[6:9], v[124:127], v[80:95]
	ds_read_b128 v[6:9], v0 offset:320
	ds_read_b128 v[128:131], v0 offset:13120
	s_waitcnt lgkmcnt(4)
	v_mfma_f32_32x32x16_bf16 v[96:111], v[136:139], v[124:127], v[96:111]
	s_waitcnt lgkmcnt(3)
	v_mfma_f32_32x32x16_bf16 v[80:95], v[2:5], v[120:123], v[80:95]
	ds_read_b128 v[2:5], v0 offset:352
	ds_read_b128 v[124:127], v0 offset:13152
	s_waitcnt lgkmcnt(4)
	v_mfma_f32_32x32x16_bf16 v[96:111], v[10:13], v[120:123], v[96:111]
	s_waitcnt lgkmcnt(3)
	v_mfma_f32_32x32x16_bf16 v[80:95], v[6:9], v[116:119], v[80:95]
	s_waitcnt lgkmcnt(2)
	v_mfma_f32_32x32x16_bf16 v[96:111], v[128:131], v[116:119], v[96:111]
	s_waitcnt lgkmcnt(1)
	v_mfma_f32_32x32x16_bf16 v[80:95], v[2:5], v[112:115], v[80:95]
	v_add_u32_e32 v0, s4, v188
	v_add_u32_e32 v6, v0, v191
	v_add_u32_e32 v6, v6, v188
	v_add_u32_e32 v15, 0x6000, v6
	v_add_u32_e32 v116, 0x7000, v6
	v_add_u32_e32 v117, 0x8000, v6
	ds_read_b128 v[2:5], v15 offset:1024
	ds_read_b128 v[10:13], v117 offset:2048
	s_nop 4
	v_max_f32_e32 v0, v81, v81
	v_max_f32_e32 v7, v80, v80
	v_max_f32_e32 v0, v7, v0
	s_waitcnt lgkmcnt(2)
	v_mfma_f32_32x32x16_bf16 v[96:111], v[124:127], v[112:115], v[96:111]
	v_max3_f32 v0, v0, v82, v83
	v_max3_f32 v0, v0, v84, v85
	v_max3_f32 v0, v0, v86, v87
	v_max3_f32 v0, v0, v88, v89
	v_max3_f32 v0, v0, v90, v91
	v_max3_f32 v0, v0, v92, v93
	v_max3_f32 v0, v0, v94, v95
	s_nop 4
	v_max3_f32 v0, v0, v96, v97
	v_max3_f32 v0, v0, v98, v99
	v_max3_f32 v0, v0, v100, v101
	v_max3_f32 v0, v0, v102, v103
	v_max3_f32 v0, v0, v104, v105
	v_max3_f32 v0, v0, v106, v107
	v_max3_f32 v0, v0, v108, v109
	v_max3_f32 v0, v0, v110, v111
	ds_bpermute_b32 v7, v189, v0
	ds_read_b128 v[112:115], v116 offset:1536
	s_waitcnt lgkmcnt(1)
	v_max3_f32 v118, v14, v0, v7
	v_sub_f32_e32 v0, v14, v118
	v_add_u32_e32 v14, 0x9000, v6
	v_exp_f32_e32 v0, v0
	ds_read_b128 v[6:9], v14 offset:2560
	v_cmp_neq_f32_e32 vcc, 1.0, v0
	s_cbranch_vccz .LBB0_1076
	v_pk_mul_f32 v[78:79], v[78:79], v[0:1] op_sel_hi:[1,0]
	v_pk_mul_f32 v[76:77], v[76:77], v[0:1] op_sel_hi:[1,0]
	v_pk_mul_f32 v[74:75], v[74:75], v[0:1] op_sel_hi:[1,0]
	v_pk_mul_f32 v[72:73], v[72:73], v[0:1] op_sel_hi:[1,0]
	v_pk_mul_f32 v[70:71], v[70:71], v[0:1] op_sel_hi:[1,0]
	v_pk_mul_f32 v[68:69], v[68:69], v[0:1] op_sel_hi:[1,0]
	v_pk_mul_f32 v[66:67], v[66:67], v[0:1] op_sel_hi:[1,0]
	v_pk_mul_f32 v[64:65], v[64:65], v[0:1] op_sel_hi:[1,0]
	v_pk_mul_f32 v[62:63], v[62:63], v[0:1] op_sel_hi:[1,0]
	v_pk_mul_f32 v[60:61], v[60:61], v[0:1] op_sel_hi:[1,0]
	v_pk_mul_f32 v[58:59], v[58:59], v[0:1] op_sel_hi:[1,0]
	v_pk_mul_f32 v[56:57], v[56:57], v[0:1] op_sel_hi:[1,0]
	v_pk_mul_f32 v[54:55], v[54:55], v[0:1] op_sel_hi:[1,0]
	v_pk_mul_f32 v[52:53], v[52:53], v[0:1] op_sel_hi:[1,0]
	v_pk_mul_f32 v[50:51], v[50:51], v[0:1] op_sel_hi:[1,0]
	v_pk_mul_f32 v[48:49], v[48:49], v[0:1] op_sel_hi:[1,0]
	v_pk_mul_f32 v[46:47], v[46:47], v[0:1] op_sel_hi:[1,0]
	v_pk_mul_f32 v[44:45], v[44:45], v[0:1] op_sel_hi:[1,0]
	v_pk_mul_f32 v[42:43], v[42:43], v[0:1] op_sel_hi:[1,0]
	v_pk_mul_f32 v[40:41], v[40:41], v[0:1] op_sel_hi:[1,0]
	v_pk_mul_f32 v[38:39], v[38:39], v[0:1] op_sel_hi:[1,0]
	v_pk_mul_f32 v[36:37], v[36:37], v[0:1] op_sel_hi:[1,0]
	v_pk_mul_f32 v[34:35], v[34:35], v[0:1] op_sel_hi:[1,0]
	v_pk_mul_f32 v[32:33], v[32:33], v[0:1] op_sel_hi:[1,0]
	v_pk_mul_f32 v[30:31], v[30:31], v[0:1] op_sel_hi:[1,0]
	v_pk_mul_f32 v[28:29], v[28:29], v[0:1] op_sel_hi:[1,0]
	v_pk_mul_f32 v[26:27], v[26:27], v[0:1] op_sel_hi:[1,0]
	v_pk_mul_f32 v[24:25], v[24:25], v[0:1] op_sel_hi:[1,0]
	v_pk_mul_f32 v[22:23], v[22:23], v[0:1] op_sel_hi:[1,0]
	v_pk_mul_f32 v[20:21], v[20:21], v[0:1] op_sel_hi:[1,0]
	v_pk_mul_f32 v[18:19], v[18:19], v[0:1] op_sel_hi:[1,0]
	v_pk_mul_f32 v[16:17], v[16:17], v[0:1] op_sel_hi:[1,0]
	s_branch .LBB0_1076
